# plus: attention epilogue gate loads prefetched together, S5 complex recurrence with packed FMAs, scan steps padded by 2 nops
# speedup vs baseline: 1.0237x; 1.0026x over previous
.LBB0_565:
	ds_bpermute_b32 v66, v207, v203
	s_lshl_b32 s58, s11, 1
	v_lshlrev_b64 v[72:73], 12, v[0:1]
	s_mov_b64 s[4:5], 0xbe00800
	s_mov_b32 s2, 0xbe00000
	s_waitcnt lgkmcnt(0)
	v_add_f32_e32 v66, v203, v66
	ds_bpermute_b32 v67, v209, v66
	s_waitcnt lgkmcnt(0)
	s_barrier
	s_add_u32 s0, s36, s58
	v_add_f32_e32 v66, v66, v67
	v_div_scale_f32 v67, s[6:7], v66, v66, 1.0
	v_rcp_f32_e32 v68, v67
	s_addc_u32 s1, s37, 0
	v_lshl_add_u64 v[72:73], s[0:1], 0, v[72:73]
	s_add_i32 s10, s10, s34
	v_fma_f32 v69, -v67, v68, 1.0
	v_fmac_f32_e32 v68, v69, v68
	v_div_scale_f32 v69, vcc, 1.0, v66, 1.0
	v_mul_f32_e32 v70, v69, v68
	v_fma_f32 v71, -v67, v70, v69
	v_fmac_f32_e32 v70, v71, v68
	v_fma_f32 v67, -v67, v70, v69
	v_div_fmas_f32 v67, v67, v68, v70
	v_div_fixup_f32 v68, v67, v66, 1.0
	v_mov_b64_e32 v[66:67], s[86:87]
	v_mad_u64_u32 v[70:71], s[6:7], v0, s97, v[66:67]
	v_lshl_add_u64 v[70:71], v[70:71], 0, s[58:59]
	v_lshlrev_b32_e32 v0, 1, v193
	v_lshl_add_u64 v[74:75], v[70:71], 0, v[0:1]
	v_lshl_add_u64 v[70:71], v[74:75], 0, s[4:5]
	v_add_co_u32_e32 v74, vcc, s2, v74
	v_pk_mul_f32 v[64:65], v[64:65], v[68:69] op_sel_hi:[1,0]
	s_nop 0
	v_addc_co_u32_e32 v75, vcc, 0, v75, vcc
	global_load_dwordx2 v[74:75], v[74:75], off offset:2048
	v_add_co_u32_e32 v146, vcc, 0x1a000, v70
	s_nop 1
	v_addc_co_u32_e32 v147, vcc, 0, v71, vcc
	global_load_dwordx2 v[114:115], v[70:71], off offset:32
	global_load_dwordx2 v[116:117], v[70:71], off offset:64
	global_load_dwordx2 v[118:119], v[70:71], off offset:96
	global_load_dwordx2 v[120:121], v[70:71], off offset:128
	global_load_dwordx2 v[122:123], v[70:71], off offset:160
	global_load_dwordx2 v[124:125], v[70:71], off offset:192
	global_load_dwordx2 v[126:127], v[70:71], off offset:224
	global_load_dwordx2 v[128:129], v[146:147], off
	global_load_dwordx2 v[130:131], v[146:147], off offset:32
	global_load_dwordx2 v[132:133], v[146:147], off offset:64
	global_load_dwordx2 v[134:135], v[146:147], off offset:96
	global_load_dwordx2 v[136:137], v[146:147], off offset:128
	global_load_dwordx2 v[138:139], v[146:147], off offset:160
	global_load_dwordx2 v[140:141], v[146:147], off offset:192
	global_load_dwordx2 v[142:143], v[146:147], off offset:224
	v_pk_mul_f32 v[62:63], v[62:63], v[68:69] op_sel_hi:[1,0]
	s_cmpk_gt_i32 s10, 0x3ff
	s_waitcnt vmcnt(15)
	v_lshlrev_b32_e32 v76, 16, v74
	v_mul_f32_e32 v69, 0xbfb8aa3b, v76
	v_exp_f32_e32 v69, v69
	v_and_b32_e32 v77, 0xffff0000, v74
	v_add_f32_e32 v69, 1.0, v69
	v_rcp_f32_e32 v78, v69
	v_mul_f32_e32 v69, 0xbfb8aa3b, v77
	v_exp_f32_e32 v69, v69
	s_nop 0
	v_add_f32_e32 v69, 1.0, v69
	v_rcp_f32_e32 v79, v69
	s_nop 0
	v_pk_mul_f32 v[76:77], v[78:79], v[76:77]
	s_nop 0
	v_pk_mul_f32 v[62:63], v[62:63], v[76:77]
	s_nop 0
	v_cvt_pk_bf16_f32 v74, v62, v63
	v_lshlrev_b32_e32 v62, 16, v75
	v_mul_f32_e32 v69, 0xbfb8aa3b, v62
	v_exp_f32_e32 v69, v69
	v_and_b32_e32 v63, 0xffff0000, v75
	v_add_f32_e32 v69, 1.0, v69
	v_rcp_f32_e32 v76, v69
	v_mul_f32_e32 v69, 0xbfb8aa3b, v63
	v_exp_f32_e32 v69, v69
	s_nop 0
	v_add_f32_e32 v69, 1.0, v69
	v_rcp_f32_e32 v77, v69
	v_pk_mul_f32 v[58:59], v[58:59], v[68:69] op_sel_hi:[1,0]
	v_pk_mul_f32 v[60:61], v[60:61], v[68:69] op_sel_hi:[1,0]
	v_pk_mul_f32 v[54:55], v[54:55], v[68:69] op_sel_hi:[1,0]
	v_pk_mul_f32 v[62:63], v[76:77], v[62:63]
	v_pk_mul_f32 v[56:57], v[56:57], v[68:69] op_sel_hi:[1,0]
	v_pk_mul_f32 v[62:63], v[64:65], v[62:63]
	v_cvt_pk_bf16_f32 v75, v62, v63
	v_lshl_add_u64 v[62:63], v[72:73], 0, v[0:1]
	global_store_dwordx2 v[62:63], v[74:75], off
	v_pk_mul_f32 v[50:51], v[50:51], v[68:69] op_sel_hi:[1,0]
	v_pk_mul_f32 v[52:53], v[52:53], v[68:69] op_sel_hi:[1,0]
	v_pk_mul_f32 v[46:47], v[46:47], v[68:69] op_sel_hi:[1,0]
	v_pk_mul_f32 v[48:49], v[48:49], v[68:69] op_sel_hi:[1,0]
	v_pk_mul_f32 v[42:43], v[42:43], v[68:69] op_sel_hi:[1,0]
	v_pk_mul_f32 v[44:45], v[44:45], v[68:69] op_sel_hi:[1,0]
	v_pk_mul_f32 v[38:39], v[38:39], v[68:69] op_sel_hi:[1,0]
	v_pk_mul_f32 v[40:41], v[40:41], v[68:69] op_sel_hi:[1,0]
	v_pk_mul_f32 v[34:35], v[34:35], v[68:69] op_sel_hi:[1,0]
	v_pk_mul_f32 v[36:37], v[36:37], v[68:69] op_sel_hi:[1,0]
	s_waitcnt vmcnt(15)
	v_mov_b32_e32 v64, v114
	v_mov_b32_e32 v65, v115
	v_lshlrev_b32_e32 v72, 16, v64
	v_and_b32_e32 v73, 0xffff0000, v64
	v_mul_f32_e32 v64, 0xbfb8aa3b, v72
	v_exp_f32_e32 v64, v64
	s_nop 0
	v_add_f32_e32 v64, 1.0, v64
	v_rcp_f32_e32 v74, v64
	v_mul_f32_e32 v64, 0xbfb8aa3b, v73
	v_exp_f32_e32 v64, v64
	s_nop 0
	v_add_f32_e32 v64, 1.0, v64
	v_rcp_f32_e32 v75, v64
	v_lshlrev_b32_e32 v64, 16, v65
	v_and_b32_e32 v65, 0xffff0000, v65
	v_pk_mul_f32 v[72:73], v[74:75], v[72:73]
	s_nop 0
	v_pk_mul_f32 v[58:59], v[58:59], v[72:73]
	s_nop 0
	v_cvt_pk_bf16_f32 v58, v58, v59
	v_mul_f32_e32 v59, 0xbfb8aa3b, v64
	v_exp_f32_e32 v59, v59
	s_nop 0
	v_add_f32_e32 v59, 1.0, v59
	v_rcp_f32_e32 v72, v59
	v_mul_f32_e32 v59, 0xbfb8aa3b, v65
	v_exp_f32_e32 v59, v59
	s_nop 0
	v_add_f32_e32 v59, 1.0, v59
	v_rcp_f32_e32 v73, v59
	s_nop 0
	v_pk_mul_f32 v[64:65], v[72:73], v[64:65]
	s_nop 0
	v_pk_mul_f32 v[60:61], v[60:61], v[64:65]
	s_nop 0
	v_cvt_pk_bf16_f32 v59, v60, v61
	global_store_dwordx2 v[62:63], v[58:59], off offset:32
	s_waitcnt vmcnt(15)
	v_mov_b32_e32 v58, v116
	v_mov_b32_e32 v59, v117
	v_lshlrev_b32_e32 v60, 16, v58
	v_and_b32_e32 v61, 0xffff0000, v58
	v_mul_f32_e32 v58, 0xbfb8aa3b, v60
	v_exp_f32_e32 v58, v58
	s_nop 0
	v_add_f32_e32 v58, 1.0, v58
	v_rcp_f32_e32 v64, v58
	v_mul_f32_e32 v58, 0xbfb8aa3b, v61
	v_exp_f32_e32 v58, v58
	s_nop 0
	v_add_f32_e32 v58, 1.0, v58
	v_rcp_f32_e32 v65, v58
	v_lshlrev_b32_e32 v58, 16, v59
	v_and_b32_e32 v59, 0xffff0000, v59
	v_pk_mul_f32 v[60:61], v[64:65], v[60:61]
	s_nop 0
	v_pk_mul_f32 v[54:55], v[54:55], v[60:61]
	s_nop 0
	v_cvt_pk_bf16_f32 v54, v54, v55
	v_mul_f32_e32 v55, 0xbfb8aa3b, v58
	v_exp_f32_e32 v55, v55
	s_nop 0
	v_add_f32_e32 v55, 1.0, v55
	v_rcp_f32_e32 v60, v55
	v_mul_f32_e32 v55, 0xbfb8aa3b, v59
	v_exp_f32_e32 v55, v55
	s_nop 0
	v_add_f32_e32 v55, 1.0, v55
	v_rcp_f32_e32 v61, v55
	s_nop 0
	v_pk_mul_f32 v[58:59], v[60:61], v[58:59]
	s_nop 0
	v_pk_mul_f32 v[56:57], v[56:57], v[58:59]
	s_nop 0
	v_cvt_pk_bf16_f32 v55, v56, v57
	global_store_dwordx2 v[62:63], v[54:55], off offset:64
	s_waitcnt vmcnt(15)
	v_mov_b32_e32 v54, v118
	v_mov_b32_e32 v55, v119
	v_lshlrev_b32_e32 v56, 16, v54
	v_and_b32_e32 v57, 0xffff0000, v54
	v_mul_f32_e32 v54, 0xbfb8aa3b, v56
	v_exp_f32_e32 v54, v54
	s_nop 0
	v_add_f32_e32 v54, 1.0, v54
	v_rcp_f32_e32 v58, v54
	v_mul_f32_e32 v54, 0xbfb8aa3b, v57
	v_exp_f32_e32 v54, v54
	s_nop 0
	v_add_f32_e32 v54, 1.0, v54
	v_rcp_f32_e32 v59, v54
	v_lshlrev_b32_e32 v54, 16, v55
	v_and_b32_e32 v55, 0xffff0000, v55
	v_pk_mul_f32 v[56:57], v[58:59], v[56:57]
	s_nop 0
	v_pk_mul_f32 v[50:51], v[50:51], v[56:57]
	s_nop 0
	v_cvt_pk_bf16_f32 v50, v50, v51
	v_mul_f32_e32 v51, 0xbfb8aa3b, v54
	v_exp_f32_e32 v51, v51
	s_nop 0
	v_add_f32_e32 v51, 1.0, v51
	v_rcp_f32_e32 v56, v51
	v_mul_f32_e32 v51, 0xbfb8aa3b, v55
	v_exp_f32_e32 v51, v51
	s_nop 0
	v_add_f32_e32 v51, 1.0, v51
	v_rcp_f32_e32 v57, v51
	s_nop 0
	v_pk_mul_f32 v[54:55], v[56:57], v[54:55]
	s_nop 0
	v_pk_mul_f32 v[52:53], v[52:53], v[54:55]
	s_nop 0
	v_cvt_pk_bf16_f32 v51, v52, v53
	global_store_dwordx2 v[62:63], v[50:51], off offset:96
	s_waitcnt vmcnt(15)
	v_mov_b32_e32 v50, v120
	v_mov_b32_e32 v51, v121
	v_lshlrev_b32_e32 v52, 16, v50
	v_and_b32_e32 v53, 0xffff0000, v50
	v_mul_f32_e32 v50, 0xbfb8aa3b, v52
	v_exp_f32_e32 v50, v50
	s_nop 0
	v_add_f32_e32 v50, 1.0, v50
	v_rcp_f32_e32 v54, v50
	v_mul_f32_e32 v50, 0xbfb8aa3b, v53
	v_exp_f32_e32 v50, v50
	s_nop 0
	v_add_f32_e32 v50, 1.0, v50
	v_rcp_f32_e32 v55, v50
	v_lshlrev_b32_e32 v50, 16, v51
	v_and_b32_e32 v51, 0xffff0000, v51
	v_pk_mul_f32 v[52:53], v[54:55], v[52:53]
	s_nop 0
	v_pk_mul_f32 v[46:47], v[46:47], v[52:53]
	s_nop 0
	v_cvt_pk_bf16_f32 v46, v46, v47
	v_mul_f32_e32 v47, 0xbfb8aa3b, v50
	v_exp_f32_e32 v47, v47
	s_nop 0
	v_add_f32_e32 v47, 1.0, v47
	v_rcp_f32_e32 v52, v47
	v_mul_f32_e32 v47, 0xbfb8aa3b, v51
	v_exp_f32_e32 v47, v47
	s_nop 0
	v_add_f32_e32 v47, 1.0, v47
	v_rcp_f32_e32 v53, v47
	s_nop 0
	v_pk_mul_f32 v[50:51], v[52:53], v[50:51]
	s_nop 0
	v_pk_mul_f32 v[48:49], v[48:49], v[50:51]
	s_nop 0
	v_cvt_pk_bf16_f32 v47, v48, v49
	global_store_dwordx2 v[62:63], v[46:47], off offset:128
	s_waitcnt vmcnt(15)
	v_mov_b32_e32 v46, v122
	v_mov_b32_e32 v47, v123
	v_lshlrev_b32_e32 v48, 16, v46
	v_and_b32_e32 v49, 0xffff0000, v46
	v_mul_f32_e32 v46, 0xbfb8aa3b, v48
	v_exp_f32_e32 v46, v46
	s_nop 0
	v_add_f32_e32 v46, 1.0, v46
	v_rcp_f32_e32 v50, v46
	v_mul_f32_e32 v46, 0xbfb8aa3b, v49
	v_exp_f32_e32 v46, v46
	s_nop 0
	v_add_f32_e32 v46, 1.0, v46
	v_rcp_f32_e32 v51, v46
	v_lshlrev_b32_e32 v46, 16, v47
	v_and_b32_e32 v47, 0xffff0000, v47
	v_pk_mul_f32 v[48:49], v[50:51], v[48:49]
	s_nop 0
	v_pk_mul_f32 v[42:43], v[42:43], v[48:49]
	s_nop 0
	v_cvt_pk_bf16_f32 v42, v42, v43
	v_mul_f32_e32 v43, 0xbfb8aa3b, v46
	v_exp_f32_e32 v43, v43
	s_nop 0
	v_add_f32_e32 v43, 1.0, v43
	v_rcp_f32_e32 v48, v43
	v_mul_f32_e32 v43, 0xbfb8aa3b, v47
	v_exp_f32_e32 v43, v43
	s_nop 0
	v_add_f32_e32 v43, 1.0, v43
	v_rcp_f32_e32 v49, v43
	s_nop 0
	v_pk_mul_f32 v[46:47], v[48:49], v[46:47]
	s_nop 0
	v_pk_mul_f32 v[44:45], v[44:45], v[46:47]
	s_nop 0
	v_cvt_pk_bf16_f32 v43, v44, v45
	global_store_dwordx2 v[62:63], v[42:43], off offset:160
	s_waitcnt vmcnt(15)
	v_mov_b32_e32 v42, v124
	v_mov_b32_e32 v43, v125
	v_lshlrev_b32_e32 v44, 16, v42
	v_and_b32_e32 v45, 0xffff0000, v42
	v_mul_f32_e32 v42, 0xbfb8aa3b, v44
	v_exp_f32_e32 v42, v42
	s_nop 0
	v_add_f32_e32 v42, 1.0, v42
	v_rcp_f32_e32 v46, v42
	v_mul_f32_e32 v42, 0xbfb8aa3b, v45
	v_exp_f32_e32 v42, v42
	s_nop 0
	v_add_f32_e32 v42, 1.0, v42
	v_rcp_f32_e32 v47, v42
	v_lshlrev_b32_e32 v42, 16, v43
	v_and_b32_e32 v43, 0xffff0000, v43
	v_pk_mul_f32 v[44:45], v[46:47], v[44:45]
	s_nop 0
	v_pk_mul_f32 v[38:39], v[38:39], v[44:45]
	s_nop 0
	v_cvt_pk_bf16_f32 v38, v38, v39
	v_mul_f32_e32 v39, 0xbfb8aa3b, v42
	v_exp_f32_e32 v39, v39
	s_nop 0
	v_add_f32_e32 v39, 1.0, v39
	v_rcp_f32_e32 v44, v39
	v_mul_f32_e32 v39, 0xbfb8aa3b, v43
	v_exp_f32_e32 v39, v39
	s_nop 0
	v_add_f32_e32 v39, 1.0, v39
	v_rcp_f32_e32 v45, v39
	s_nop 0
	v_pk_mul_f32 v[42:43], v[44:45], v[42:43]
	s_nop 0
	v_pk_mul_f32 v[40:41], v[40:41], v[42:43]
	s_nop 0
	v_cvt_pk_bf16_f32 v39, v40, v41
	global_store_dwordx2 v[62:63], v[38:39], off offset:192
	s_waitcnt vmcnt(15)
	v_mov_b32_e32 v38, v126
	v_mov_b32_e32 v39, v127
	v_lshlrev_b32_e32 v40, 16, v38
	v_and_b32_e32 v41, 0xffff0000, v38
	v_mul_f32_e32 v38, 0xbfb8aa3b, v40
	v_exp_f32_e32 v38, v38
	s_nop 0
	v_add_f32_e32 v38, 1.0, v38
	v_rcp_f32_e32 v42, v38
	v_mul_f32_e32 v38, 0xbfb8aa3b, v41
	v_exp_f32_e32 v38, v38
	s_nop 0
	v_add_f32_e32 v38, 1.0, v38
	v_rcp_f32_e32 v43, v38
	v_lshlrev_b32_e32 v38, 16, v39
	v_and_b32_e32 v39, 0xffff0000, v39
	v_pk_mul_f32 v[40:41], v[42:43], v[40:41]
	s_nop 0
	v_pk_mul_f32 v[34:35], v[34:35], v[40:41]
	s_nop 0
	v_cvt_pk_bf16_f32 v34, v34, v35
	v_mul_f32_e32 v35, 0xbfb8aa3b, v38
	v_exp_f32_e32 v35, v35
	s_nop 0
	v_add_f32_e32 v35, 1.0, v35
	v_rcp_f32_e32 v40, v35
	v_mul_f32_e32 v35, 0xbfb8aa3b, v39
	v_exp_f32_e32 v35, v35
	s_nop 0
	v_add_f32_e32 v35, 1.0, v35
	v_rcp_f32_e32 v41, v35
	s_nop 0
	v_pk_mul_f32 v[38:39], v[40:41], v[38:39]
	s_nop 0
	v_pk_mul_f32 v[36:37], v[36:37], v[38:39]
	s_nop 0
	v_cvt_pk_bf16_f32 v35, v36, v37
	global_store_dwordx2 v[62:63], v[34:35], off offset:224
	ds_bpermute_b32 v34, v207, v191
	s_waitcnt lgkmcnt(0)
	v_add_f32_e32 v34, v191, v34
	ds_bpermute_b32 v35, v209, v34
	s_waitcnt lgkmcnt(0)
	v_add_f32_e32 v34, v34, v35
	v_div_scale_f32 v35, s[6:7], v34, v34, 1.0
	v_rcp_f32_e32 v36, v35
	s_nop 0
	v_fma_f32 v37, -v35, v36, 1.0
	v_fmac_f32_e32 v36, v37, v36
	v_div_scale_f32 v37, vcc, 1.0, v34, 1.0
	v_mul_f32_e32 v38, v37, v36
	v_fma_f32 v39, -v35, v38, v37
	v_fmac_f32_e32 v38, v39, v36
	v_fma_f32 v35, -v35, v38, v37
	v_div_fmas_f32 v35, v35, v36, v38
	v_mad_u64_u32 v[36:37], s[6:7], v188, s97, v[66:67]
	v_lshl_add_u64 v[36:37], v[36:37], 0, s[58:59]
	v_lshl_add_u64 v[40:41], v[36:37], 0, v[0:1]
	v_lshl_add_u64 v[36:37], v[40:41], 0, s[4:5]
	v_add_co_u32_e32 v40, vcc, s2, v40
	v_div_fixup_f32 v34, v35, v34, 1.0
	s_nop 0
	v_addc_co_u32_e32 v41, vcc, 0, v41, vcc
	v_pk_mul_f32 v[32:33], v[32:33], v[34:35] op_sel_hi:[1,0]
	v_pk_mul_f32 v[30:31], v[30:31], v[34:35] op_sel_hi:[1,0]
	v_lshlrev_b64 v[38:39], 12, v[188:189]
	v_lshl_add_u64 v[38:39], s[0:1], 0, v[38:39]
	s_waitcnt vmcnt(15)
	v_mov_b32_e32 v40, v128
	v_mov_b32_e32 v41, v129
	v_lshlrev_b32_e32 v42, 16, v40
	v_mul_f32_e32 v35, 0xbfb8aa3b, v42
	v_exp_f32_e32 v35, v35
	v_and_b32_e32 v43, 0xffff0000, v40
	v_add_f32_e32 v35, 1.0, v35
	v_rcp_f32_e32 v44, v35
	v_mul_f32_e32 v35, 0xbfb8aa3b, v43
	v_exp_f32_e32 v35, v35
	s_nop 0
	v_add_f32_e32 v35, 1.0, v35
	v_rcp_f32_e32 v45, v35
	s_nop 0
	v_pk_mul_f32 v[42:43], v[44:45], v[42:43]
	s_nop 0
	v_pk_mul_f32 v[30:31], v[30:31], v[42:43]
	s_nop 0
	v_cvt_pk_bf16_f32 v40, v30, v31
	v_lshlrev_b32_e32 v30, 16, v41
	v_mul_f32_e32 v35, 0xbfb8aa3b, v30
	v_exp_f32_e32 v35, v35
	v_and_b32_e32 v31, 0xffff0000, v41
	v_add_f32_e32 v35, 1.0, v35
	v_rcp_f32_e32 v42, v35
	v_mul_f32_e32 v35, 0xbfb8aa3b, v31
	v_exp_f32_e32 v35, v35
	s_nop 0
	v_add_f32_e32 v35, 1.0, v35
	v_rcp_f32_e32 v43, v35
	v_pk_mul_f32 v[26:27], v[26:27], v[34:35] op_sel_hi:[1,0]
	v_pk_mul_f32 v[28:29], v[28:29], v[34:35] op_sel_hi:[1,0]
	v_pk_mul_f32 v[22:23], v[22:23], v[34:35] op_sel_hi:[1,0]
	v_pk_mul_f32 v[30:31], v[42:43], v[30:31]
	v_pk_mul_f32 v[24:25], v[24:25], v[34:35] op_sel_hi:[1,0]
	v_pk_mul_f32 v[30:31], v[32:33], v[30:31]
	v_cvt_pk_bf16_f32 v41, v30, v31
	v_lshl_add_u64 v[30:31], v[38:39], 0, v[0:1]
	global_store_dwordx2 v[30:31], v[40:41], off
	v_pk_mul_f32 v[18:19], v[18:19], v[34:35] op_sel_hi:[1,0]
	v_pk_mul_f32 v[20:21], v[20:21], v[34:35] op_sel_hi:[1,0]
	v_pk_mul_f32 v[14:15], v[14:15], v[34:35] op_sel_hi:[1,0]
	v_pk_mul_f32 v[16:17], v[16:17], v[34:35] op_sel_hi:[1,0]
	v_pk_mul_f32 v[10:11], v[10:11], v[34:35] op_sel_hi:[1,0]
	v_pk_mul_f32 v[12:13], v[12:13], v[34:35] op_sel_hi:[1,0]
	v_pk_mul_f32 v[6:7], v[6:7], v[34:35] op_sel_hi:[1,0]
	v_pk_mul_f32 v[8:9], v[8:9], v[34:35] op_sel_hi:[1,0]
	v_pk_mul_f32 v[2:3], v[2:3], v[34:35] op_sel_hi:[1,0]
	v_pk_mul_f32 v[4:5], v[4:5], v[34:35] op_sel_hi:[1,0]
	s_waitcnt vmcnt(15)
	v_mov_b32_e32 v32, v130
	v_mov_b32_e32 v33, v131
	v_lshlrev_b32_e32 v38, 16, v32
	v_mul_f32_e32 v0, 0xbfb8aa3b, v38
	v_exp_f32_e32 v0, v0
	v_and_b32_e32 v39, 0xffff0000, v32
	v_lshlrev_b32_e32 v32, 16, v33
	v_and_b32_e32 v33, 0xffff0000, v33
	v_add_f32_e32 v0, 1.0, v0
	v_rcp_f32_e32 v40, v0
	v_mul_f32_e32 v0, 0xbfb8aa3b, v39
	v_exp_f32_e32 v0, v0
	s_nop 0
	v_add_f32_e32 v0, 1.0, v0
	v_rcp_f32_e32 v41, v0
	v_mul_f32_e32 v0, 0xbfb8aa3b, v32
	v_exp_f32_e32 v0, v0
	v_pk_mul_f32 v[38:39], v[40:41], v[38:39]
	s_nop 0
	v_pk_mul_f32 v[26:27], v[26:27], v[38:39]
	v_add_f32_e32 v0, 1.0, v0
	v_rcp_f32_e32 v38, v0
	v_mul_f32_e32 v0, 0xbfb8aa3b, v33
	v_exp_f32_e32 v0, v0
	v_cvt_pk_bf16_f32 v26, v26, v27
	v_add_f32_e32 v0, 1.0, v0
	v_rcp_f32_e32 v39, v0
	s_nop 0
	v_pk_mul_f32 v[32:33], v[38:39], v[32:33]
	s_nop 0
	v_pk_mul_f32 v[28:29], v[28:29], v[32:33]
	s_nop 0
	v_cvt_pk_bf16_f32 v27, v28, v29
	global_store_dwordx2 v[30:31], v[26:27], off offset:32
	s_waitcnt vmcnt(15)
	v_mov_b32_e32 v26, v132
	v_mov_b32_e32 v27, v133
	v_lshlrev_b32_e32 v28, 16, v26
	v_mul_f32_e32 v0, 0xbfb8aa3b, v28
	v_exp_f32_e32 v0, v0
	v_and_b32_e32 v29, 0xffff0000, v26
	v_lshlrev_b32_e32 v26, 16, v27
	v_and_b32_e32 v27, 0xffff0000, v27
	v_add_f32_e32 v0, 1.0, v0
	v_rcp_f32_e32 v32, v0
	v_mul_f32_e32 v0, 0xbfb8aa3b, v29
	v_exp_f32_e32 v0, v0
	s_nop 0
	v_add_f32_e32 v0, 1.0, v0
	v_rcp_f32_e32 v33, v0
	v_mul_f32_e32 v0, 0xbfb8aa3b, v26
	v_exp_f32_e32 v0, v0
	v_pk_mul_f32 v[28:29], v[32:33], v[28:29]
	s_nop 0
	v_pk_mul_f32 v[22:23], v[22:23], v[28:29]
	v_add_f32_e32 v0, 1.0, v0
	v_rcp_f32_e32 v28, v0
	v_mul_f32_e32 v0, 0xbfb8aa3b, v27
	v_exp_f32_e32 v0, v0
	v_cvt_pk_bf16_f32 v22, v22, v23
	v_add_f32_e32 v0, 1.0, v0
	v_rcp_f32_e32 v29, v0
	s_nop 0
	v_pk_mul_f32 v[26:27], v[28:29], v[26:27]
	s_nop 0
	v_pk_mul_f32 v[24:25], v[24:25], v[26:27]
	s_nop 0
	v_cvt_pk_bf16_f32 v23, v24, v25
	global_store_dwordx2 v[30:31], v[22:23], off offset:64
	s_waitcnt vmcnt(15)
	v_mov_b32_e32 v22, v134
	v_mov_b32_e32 v23, v135
	v_lshlrev_b32_e32 v24, 16, v22
	v_mul_f32_e32 v0, 0xbfb8aa3b, v24
	v_exp_f32_e32 v0, v0
	v_and_b32_e32 v25, 0xffff0000, v22
	v_lshlrev_b32_e32 v22, 16, v23
	v_and_b32_e32 v23, 0xffff0000, v23
	v_add_f32_e32 v0, 1.0, v0
	v_rcp_f32_e32 v26, v0
	v_mul_f32_e32 v0, 0xbfb8aa3b, v25
	v_exp_f32_e32 v0, v0
	s_nop 0
	v_add_f32_e32 v0, 1.0, v0
	v_rcp_f32_e32 v27, v0
	v_mul_f32_e32 v0, 0xbfb8aa3b, v22
	v_exp_f32_e32 v0, v0
	v_pk_mul_f32 v[24:25], v[26:27], v[24:25]
	s_nop 0
	v_pk_mul_f32 v[18:19], v[18:19], v[24:25]
	v_add_f32_e32 v0, 1.0, v0
	v_rcp_f32_e32 v24, v0
	v_mul_f32_e32 v0, 0xbfb8aa3b, v23
	v_exp_f32_e32 v0, v0
	v_cvt_pk_bf16_f32 v18, v18, v19
	v_add_f32_e32 v0, 1.0, v0
	v_rcp_f32_e32 v25, v0
	s_nop 0
	v_pk_mul_f32 v[22:23], v[24:25], v[22:23]
	s_nop 0
	v_pk_mul_f32 v[20:21], v[20:21], v[22:23]
	s_nop 0
	v_cvt_pk_bf16_f32 v19, v20, v21
	global_store_dwordx2 v[30:31], v[18:19], off offset:96
	s_waitcnt vmcnt(15)
	v_mov_b32_e32 v18, v136
	v_mov_b32_e32 v19, v137
	v_lshlrev_b32_e32 v20, 16, v18
	v_mul_f32_e32 v0, 0xbfb8aa3b, v20
	v_exp_f32_e32 v0, v0
	v_and_b32_e32 v21, 0xffff0000, v18
	v_lshlrev_b32_e32 v18, 16, v19
	v_and_b32_e32 v19, 0xffff0000, v19
	v_add_f32_e32 v0, 1.0, v0
	v_rcp_f32_e32 v22, v0
	v_mul_f32_e32 v0, 0xbfb8aa3b, v21
	v_exp_f32_e32 v0, v0
	s_nop 0
	v_add_f32_e32 v0, 1.0, v0
	v_rcp_f32_e32 v23, v0
	v_mul_f32_e32 v0, 0xbfb8aa3b, v18
	v_exp_f32_e32 v0, v0
	v_pk_mul_f32 v[20:21], v[22:23], v[20:21]
	s_nop 0
	v_pk_mul_f32 v[14:15], v[14:15], v[20:21]
	v_add_f32_e32 v0, 1.0, v0
	v_rcp_f32_e32 v20, v0
	v_mul_f32_e32 v0, 0xbfb8aa3b, v19
	v_exp_f32_e32 v0, v0
	v_cvt_pk_bf16_f32 v14, v14, v15
	v_add_f32_e32 v0, 1.0, v0
	v_rcp_f32_e32 v21, v0
	s_nop 0
	v_pk_mul_f32 v[18:19], v[20:21], v[18:19]
	s_nop 0
	v_pk_mul_f32 v[16:17], v[16:17], v[18:19]
	s_nop 0
	v_cvt_pk_bf16_f32 v15, v16, v17
	global_store_dwordx2 v[30:31], v[14:15], off offset:128
	s_waitcnt vmcnt(15)
	v_mov_b32_e32 v14, v138
	v_mov_b32_e32 v15, v139
	v_lshlrev_b32_e32 v16, 16, v14
	v_mul_f32_e32 v0, 0xbfb8aa3b, v16
	v_exp_f32_e32 v0, v0
	v_and_b32_e32 v17, 0xffff0000, v14
	v_lshlrev_b32_e32 v14, 16, v15
	v_and_b32_e32 v15, 0xffff0000, v15
	v_add_f32_e32 v0, 1.0, v0
	v_rcp_f32_e32 v18, v0
	v_mul_f32_e32 v0, 0xbfb8aa3b, v17
	v_exp_f32_e32 v0, v0
	s_nop 0
	v_add_f32_e32 v0, 1.0, v0
	v_rcp_f32_e32 v19, v0
	v_mul_f32_e32 v0, 0xbfb8aa3b, v14
	v_exp_f32_e32 v0, v0
	v_pk_mul_f32 v[16:17], v[18:19], v[16:17]
	s_nop 0
	v_pk_mul_f32 v[10:11], v[10:11], v[16:17]
	v_add_f32_e32 v0, 1.0, v0
	v_rcp_f32_e32 v16, v0
	v_mul_f32_e32 v0, 0xbfb8aa3b, v15
	v_exp_f32_e32 v0, v0
	v_cvt_pk_bf16_f32 v10, v10, v11
	v_add_f32_e32 v0, 1.0, v0
	v_rcp_f32_e32 v17, v0
	s_nop 0
	v_pk_mul_f32 v[14:15], v[16:17], v[14:15]
	s_nop 0
	v_pk_mul_f32 v[12:13], v[12:13], v[14:15]
	s_nop 0
	v_cvt_pk_bf16_f32 v11, v12, v13
	global_store_dwordx2 v[30:31], v[10:11], off offset:160
	s_waitcnt vmcnt(15)
	v_mov_b32_e32 v10, v140
	v_mov_b32_e32 v11, v141
	v_lshlrev_b32_e32 v12, 16, v10
	v_mul_f32_e32 v0, 0xbfb8aa3b, v12
	v_exp_f32_e32 v0, v0
	v_and_b32_e32 v13, 0xffff0000, v10
	v_lshlrev_b32_e32 v10, 16, v11
	v_and_b32_e32 v11, 0xffff0000, v11
	v_add_f32_e32 v0, 1.0, v0
	v_rcp_f32_e32 v14, v0
	v_mul_f32_e32 v0, 0xbfb8aa3b, v13
	v_exp_f32_e32 v0, v0
	s_nop 0
	v_add_f32_e32 v0, 1.0, v0
	v_rcp_f32_e32 v15, v0
	v_mul_f32_e32 v0, 0xbfb8aa3b, v10
	v_exp_f32_e32 v0, v0
	v_pk_mul_f32 v[12:13], v[14:15], v[12:13]
	s_nop 0
	v_pk_mul_f32 v[6:7], v[6:7], v[12:13]
	v_add_f32_e32 v0, 1.0, v0
	v_rcp_f32_e32 v12, v0
	v_mul_f32_e32 v0, 0xbfb8aa3b, v11
	v_exp_f32_e32 v0, v0
	v_cvt_pk_bf16_f32 v6, v6, v7
	v_add_f32_e32 v0, 1.0, v0
	v_rcp_f32_e32 v13, v0
	s_nop 0
	v_pk_mul_f32 v[10:11], v[12:13], v[10:11]
	s_nop 0
	v_pk_mul_f32 v[8:9], v[8:9], v[10:11]
	s_nop 0
	v_cvt_pk_bf16_f32 v7, v8, v9
	global_store_dwordx2 v[30:31], v[6:7], off offset:192
	s_waitcnt vmcnt(15)
	v_mov_b32_e32 v6, v142
	v_mov_b32_e32 v7, v143
	v_lshlrev_b32_e32 v8, 16, v6
	v_mul_f32_e32 v0, 0xbfb8aa3b, v8
	v_exp_f32_e32 v0, v0
	v_and_b32_e32 v9, 0xffff0000, v6
	v_lshlrev_b32_e32 v6, 16, v7
	v_and_b32_e32 v7, 0xffff0000, v7
	v_add_f32_e32 v0, 1.0, v0
	v_rcp_f32_e32 v10, v0
	v_mul_f32_e32 v0, 0xbfb8aa3b, v9
	v_exp_f32_e32 v0, v0
	s_nop 0
	v_add_f32_e32 v0, 1.0, v0
	v_rcp_f32_e32 v11, v0
	v_mul_f32_e32 v0, 0xbfb8aa3b, v6
	v_exp_f32_e32 v0, v0
	v_pk_mul_f32 v[8:9], v[10:11], v[8:9]
	s_nop 0
	v_pk_mul_f32 v[2:3], v[2:3], v[8:9]
	v_add_f32_e32 v0, 1.0, v0
	v_rcp_f32_e32 v8, v0
	v_mul_f32_e32 v0, 0xbfb8aa3b, v7
	v_exp_f32_e32 v0, v0
	v_cvt_pk_bf16_f32 v2, v2, v3
	v_add_f32_e32 v0, 1.0, v0
	v_rcp_f32_e32 v9, v0
	s_nop 0
	v_pk_mul_f32 v[6:7], v[8:9], v[6:7]
	s_nop 0
	v_pk_mul_f32 v[4:5], v[4:5], v[6:7]
	s_nop 0
	v_cvt_pk_bf16_f32 v3, v4, v5
	global_store_dwordx2 v[30:31], v[2:3], off offset:224
	s_cbranch_scc1 .LBB0_561

.LBB0_876:
	s_or_b64 exec, exec, s[42:43]
	v_add_f32_e32 v10, v55, v55
	v_mul_f32_e32 v0, v109, v109
	v_mul_f32_e32 v10, v109, v10
	v_fma_f32 v0, v55, v55, -v0
	v_mul_f32_e32 v11, v10, v10
	v_fma_f32 v11, v0, v0, -v11
	v_add_f32_e32 v0, v0, v0
	v_mul_f32_e32 v0, v10, v0
	v_mul_f32_e32 v10, v0, v0
	v_fma_f32 v10, v11, v11, -v10
	v_add_f32_e32 v11, v11, v11
	v_mul_f32_e32 v59, v0, v11
	v_mul_f32_e32 v0, v59, v59
	v_lshlrev_b32_e32 v111, 2, v111
	v_add_f32_e32 v121, v10, v10
	v_cvt_pk_bf16_f32 v6, v6, v7
	v_cvt_pk_bf16_f32 v7, v8, v9
	v_cvt_pk_bf16_f32 v8, v56, v57
	v_cvt_pk_bf16_f32 v9, v16, v17
	v_fma_f32 v56, v10, v10, -v0
	s_waitcnt vmcnt(6)
	v_cvt_pk_bf16_f32 v10, v42, v43
	s_waitcnt vmcnt(5)
	v_cvt_pk_bf16_f32 v16, v34, v35
	v_or_b32_e32 v42, s55, v111
	v_mov_b64_e32 v[34:35], s[22:23]
	v_cvt_pk_bf16_f32 v17, v36, v37
	v_mad_i64_i32 v[36:37], s[42:43], v42, s48, v[34:35]
	v_lshlrev_b32_e32 v0, 1, v58
	v_cvt_pk_bf16_f32 v12, v12, v13
	v_cvt_pk_bf16_f32 v13, v14, v15
	s_waitcnt vmcnt(4)
	v_cvt_pk_bf16_f32 v14, v38, v39
	v_lshl_add_u64 v[36:37], v[36:37], 0, v[0:1]
	v_lshlrev_b32_e32 v122, 1, v54
	v_mov_b32_e32 v123, v1
	v_or_b32_e32 v38, 1, v42
	v_lshl_add_u64 v[36:37], v[36:37], 0, v[122:123]
	s_movk_i32 s2, 0x2000
	v_mad_i64_i32 v[38:39], s[42:43], v38, s48, v[34:35]
	v_cvt_pk_bf16_f32 v15, v40, v41
	v_add_co_u32_e32 v36, vcc, s2, v36
	v_lshl_add_u64 v[38:39], v[38:39], 0, v[0:1]
	v_or_b32_e32 v40, 2, v42
	v_addc_co_u32_e32 v37, vcc, 0, v37, vcc
	v_lshl_add_u64 v[38:39], v[38:39], 0, v[122:123]
	v_mad_i64_i32 v[40:41], s[42:43], v40, s48, v[34:35]
	v_add_co_u32_e32 v38, vcc, s2, v38
	v_lshl_add_u64 v[40:41], v[40:41], 0, v[0:1]
	v_or_b32_e32 v42, 3, v42
	v_addc_co_u32_e32 v39, vcc, 0, v39, vcc
	v_lshl_add_u64 v[40:41], v[40:41], 0, v[122:123]
	v_mad_i64_i32 v[34:35], s[42:43], v42, s48, v[34:35]
	v_add_co_u32_e32 v40, vcc, s2, v40
	v_lshl_add_u64 v[34:35], v[34:35], 0, v[0:1]
	s_nop 0
	v_addc_co_u32_e32 v41, vcc, 0, v41, vcc
	v_lshl_add_u64 v[34:35], v[34:35], 0, v[122:123]
	v_add_co_u32_e32 v34, vcc, s2, v34
	v_readlane_b32 s2, v250, 3
	s_nop 0
	v_addc_co_u32_e32 v35, vcc, 0, v35, vcc
	global_load_ushort v112, v[36:37], off
	global_load_ushort v113, v[38:39], off
	global_load_ushort v114, v[40:41], off
	global_load_ushort v115, v[34:35], off
	s_waitcnt vmcnt(7)
	v_xor_b32_e32 v33, 0x80000000, v33
	v_xor_b32_e32 v32, 0x80000000, v32
	v_xor_b32_e32 v31, 0x80000000, v31
	v_xor_b32_e32 v30, 0x80000000, v30
	s_waitcnt vmcnt(6)
	v_xor_b32_e32 v21, 0x80000000, v21
	v_xor_b32_e32 v20, 0x80000000, v20
	v_xor_b32_e32 v19, 0x80000000, v19
	v_xor_b32_e32 v18, 0x80000000, v18
	s_waitcnt vmcnt(5)
	v_xor_b32_e32 v29, 0x80000000, v29
	v_xor_b32_e32 v28, 0x80000000, v28
	v_xor_b32_e32 v27, 0x80000000, v27
	v_xor_b32_e32 v26, 0x80000000, v26
	s_waitcnt vmcnt(4)
	v_xor_b32_e32 v25, 0x80000000, v25
	v_xor_b32_e32 v24, 0x80000000, v24
	v_xor_b32_e32 v23, 0x80000000, v23
	v_xor_b32_e32 v22, 0x80000000, v22
	v_mul_f32_e32 v58, v59, v121
	v_cvt_pk_bf16_f32 v42, v70, v71
	v_cvt_pk_bf16_f32 v50, v50, v51
	v_cvt_pk_bf16_f32 v51, v52, v53
	v_cvt_pk_bf16_f32 v53, v60, v61
	v_lshl_add_u64 v[60:61], s[56:57], 0, v[0:1]
	v_mul_f32_e32 v70, 0, v55
	s_add_i32 s2, s2, s24
	v_cvt_pk_bf16_f32 v11, v44, v45
	v_cvt_pk_bf16_f32 v18, v18, v19
	v_cvt_pk_bf16_f32 v19, v20, v21
	v_cvt_pk_bf16_f32 v20, v30, v31
	v_cvt_pk_bf16_f32 v21, v32, v33
	v_cvt_pk_bf16_f32 v22, v22, v23
	v_cvt_pk_bf16_f32 v23, v24, v25
	v_cvt_pk_bf16_f32 v24, v26, v27
	v_cvt_pk_bf16_f32 v25, v28, v29
	v_add_u32_e32 v116, 0, v116
	v_cvt_pk_bf16_f32 v26, v102, v103
	v_cvt_pk_bf16_f32 v27, v100, v101
	v_cvt_pk_bf16_f32 v28, v106, v107
	v_cvt_pk_bf16_f32 v29, v104, v105
	v_cvt_pk_bf16_f32 v30, v88, v89
	v_cvt_pk_bf16_f32 v31, v94, v95
	v_cvt_pk_bf16_f32 v32, v98, v99
	v_cvt_pk_bf16_f32 v33, v96, v97
	v_cvt_pk_bf16_f32 v34, v86, v87
	v_cvt_pk_bf16_f32 v35, v84, v85
	v_cvt_pk_bf16_f32 v36, v92, v93
	v_cvt_pk_bf16_f32 v37, v90, v91
	v_cvt_pk_bf16_f32 v38, v72, v73
	v_cvt_pk_bf16_f32 v39, v78, v79
	v_cvt_pk_bf16_f32 v40, v82, v83
	v_cvt_pk_bf16_f32 v41, v80, v81
	v_cvt_pk_bf16_f32 v43, v68, v69
	v_cvt_pk_bf16_f32 v44, v76, v77
	v_cvt_pk_bf16_f32 v45, v74, v75
	v_cvt_pk_bf16_f32 v46, v46, v47
	v_cvt_pk_bf16_f32 v47, v48, v49
	v_cvt_pk_bf16_f32 v48, v66, v67
	v_cvt_pk_bf16_f32 v49, v64, v65
	v_cvt_pk_bf16_f32 v52, v62, v63
	s_mov_b32 s54, 0
	v_lshl_add_u64 v[60:61], v[60:61], 0, v[122:123]
	s_add_i32 s55, s55, 32
	v_fmamk_f32 v71, v109, 0x80000000, v70
	v_fmac_f32_e32 v70, 0, v109
	v_mov_b32_e32 v57, v56
	v_mov_b32_e32 v59, v58
	v_add_u32_e32 v72, s2, v111
	v_mov_b32_e32 v66, v1
	v_mov_b32_e32 v67, v1
	v_mov_b32_e32 v63, 0
	s_movk_i32 s58, 0xfc00
	v_add_u32_e32 v73, 0, v119
	v_add_u32_e32 v74, 0, v120
	v_add_u32_e32 v75, 0, v118
	v_lshlrev_b32_e32 v62, 1, v108
	v_lshlrev_b32_e32 v64, 1, v54
	v_add_u32_e32 v76, 0, v117
	s_mov_b32 s68, 0
	v_mov_b32_e32 v92, 0
	v_mov_b32_e32 v91, 0
	v_mov_b32_e32 v65, 0
	s_mov_b32 s69, 0
	s_waitcnt vmcnt(0)
	v_mov_b32_e32 v140, v112
	v_mov_b32_e32 v141, v113
	v_mov_b32_e32 v142, v114
	v_mov_b32_e32 v143, v115
	v_mov_b32_e32 v144, v55
	v_mov_b32_e32 v145, v55
	v_xor_b32_e32 v146, 0x80000000, v109
	v_mov_b32_e32 v147, v109
	s_branch .LBB0_879
.LBB0_877:
	s_or_b64 exec, exec, s[42:43]
	v_or_b32_e32 v63, s2, v111
	v_mov_b64_e32 v[68:69], s[22:23]
	v_mad_i64_i32 v[92:93], s[24:25], v63, s48, v[68:69]
	v_lshl_add_u64 v[92:93], v[92:93], 0, v[0:1]
	v_mov_b32_e32 v65, v1
	v_lshl_add_u64 v[92:93], v[92:93], 0, v[64:65]
	v_add_co_u32_e32 v92, vcc, 0x2000, v92
	v_or_b32_e32 v91, 1, v63
	s_nop 0
	v_addc_co_u32_e32 v93, vcc, 0, v93, vcc
	global_load_ushort v140, v[92:93], off
	v_mad_i64_i32 v[92:93], s[24:25], v91, s48, v[68:69]
	v_lshl_add_u64 v[92:93], v[92:93], 0, v[0:1]
	v_lshl_add_u64 v[92:93], v[92:93], 0, v[64:65]
	v_add_co_u32_e32 v92, vcc, 0x2000, v92
	v_or_b32_e32 v91, 2, v63
	s_nop 0
	v_addc_co_u32_e32 v93, vcc, 0, v93, vcc
	global_load_ushort v141, v[92:93], off
	v_mad_i64_i32 v[92:93], s[24:25], v91, s48, v[68:69]
	v_lshl_add_u64 v[92:93], v[92:93], 0, v[0:1]
	v_or_b32_e32 v63, 3, v63
	v_lshl_add_u64 v[92:93], v[92:93], 0, v[64:65]
	v_mad_i64_i32 v[68:69], s[24:25], v63, s48, v[68:69]
	v_add_co_u32_e32 v92, vcc, 0x2000, v92
	v_lshl_add_u64 v[68:69], v[68:69], 0, v[0:1]
	s_nop 0
	v_addc_co_u32_e32 v93, vcc, 0, v93, vcc
	v_lshl_add_u64 v[68:69], v[68:69], 0, v[64:65]
	v_add_co_u32_e32 v68, vcc, 0x2000, v68
	global_load_ushort v142, v[92:93], off
	s_nop 0
	v_addc_co_u32_e32 v69, vcc, 0, v69, vcc
	global_load_ushort v143, v[68:69], off
	s_waitcnt lgkmcnt(0)
	ds_read2st64_b32 v[124:125], v76 offset1:1
	ds_read2_b32 v[126:127], v76 offset0:132 offset1:196
	ds_read2st64_b32 v[128:129], v90 offset0:4 offset1:5
	ds_read2st64_b32 v[130:131], v89 offset0:6 offset1:7
	ds_read2st64_b32 v[132:133], v88 offset0:8 offset1:9
	ds_read2st64_b32 v[134:135], v87 offset0:10 offset1:11
	ds_read2st64_b32 v[136:137], v86 offset0:12 offset1:13
	ds_read2st64_b32 v[138:139], v85 offset0:14 offset1:15
	s_and_b32 s2, s68, 2
	s_add_i32 s2, s2, s96
	v_mov_b32_e32 v92, v114
	v_mov_b32_e32 v148, 0
	v_mov_b32_e32 v149, 0
	s_waitcnt lgkmcnt(7)
	v_pk_fma_f32 v[124:125], v[148:149], v[144:145], v[124:125]
	v_pk_fma_f32 v[148:149], v[148:149], v[146:147], v[124:125] op_sel:[1,0,0] op_sel_hi:[0,1,1]
	ds_read2st64_b32 v[124:125], v84 offset0:16 offset1:17
	s_waitcnt lgkmcnt(7)
	v_pk_fma_f32 v[126:127], v[148:149], v[144:145], v[126:127]
	v_pk_fma_f32 v[148:149], v[148:149], v[146:147], v[126:127] op_sel:[1,0,0] op_sel_hi:[0,1,1]
	ds_read2st64_b32 v[126:127], v83 offset0:18 offset1:19
	s_waitcnt lgkmcnt(7)
	v_pk_fma_f32 v[128:129], v[148:149], v[144:145], v[128:129]
	v_pk_fma_f32 v[148:149], v[148:149], v[146:147], v[128:129] op_sel:[1,0,0] op_sel_hi:[0,1,1]
	ds_read2st64_b32 v[128:129], v82 offset0:20 offset1:21
	s_waitcnt lgkmcnt(7)
	v_pk_fma_f32 v[130:131], v[148:149], v[144:145], v[130:131]
	v_pk_fma_f32 v[148:149], v[148:149], v[146:147], v[130:131] op_sel:[1,0,0] op_sel_hi:[0,1,1]
	ds_read2st64_b32 v[130:131], v81 offset0:22 offset1:23
	s_waitcnt lgkmcnt(7)
	v_pk_fma_f32 v[132:133], v[148:149], v[144:145], v[132:133]
	v_pk_fma_f32 v[148:149], v[148:149], v[146:147], v[132:133] op_sel:[1,0,0] op_sel_hi:[0,1,1]
	ds_read2st64_b32 v[132:133], v80 offset0:24 offset1:25
	s_waitcnt lgkmcnt(7)
	v_pk_fma_f32 v[134:135], v[148:149], v[144:145], v[134:135]
	v_pk_fma_f32 v[148:149], v[148:149], v[146:147], v[134:135] op_sel:[1,0,0] op_sel_hi:[0,1,1]
	ds_read2st64_b32 v[134:135], v79 offset0:26 offset1:27
	s_waitcnt lgkmcnt(7)
	v_pk_fma_f32 v[136:137], v[148:149], v[144:145], v[136:137]
	v_pk_fma_f32 v[148:149], v[148:149], v[146:147], v[136:137] op_sel:[1,0,0] op_sel_hi:[0,1,1]
	ds_read2st64_b32 v[136:137], v78 offset0:28 offset1:29
	s_waitcnt lgkmcnt(7)
	v_pk_fma_f32 v[138:139], v[148:149], v[144:145], v[138:139]
	v_pk_fma_f32 v[148:149], v[148:149], v[146:147], v[138:139] op_sel:[1,0,0] op_sel_hi:[0,1,1]
	ds_read2st64_b32 v[138:139], v77 offset0:30 offset1:31
	s_waitcnt lgkmcnt(7)
	v_pk_fma_f32 v[124:125], v[148:149], v[144:145], v[124:125]
	v_pk_fma_f32 v[148:149], v[148:149], v[146:147], v[124:125] op_sel:[1,0,0] op_sel_hi:[0,1,1]
	s_waitcnt lgkmcnt(6)
	v_pk_fma_f32 v[126:127], v[148:149], v[144:145], v[126:127]
	v_pk_fma_f32 v[148:149], v[148:149], v[146:147], v[126:127] op_sel:[1,0,0] op_sel_hi:[0,1,1]
	s_waitcnt lgkmcnt(5)
	v_pk_fma_f32 v[128:129], v[148:149], v[144:145], v[128:129]
	v_pk_fma_f32 v[148:149], v[148:149], v[146:147], v[128:129] op_sel:[1,0,0] op_sel_hi:[0,1,1]
	s_waitcnt lgkmcnt(4)
	v_pk_fma_f32 v[130:131], v[148:149], v[144:145], v[130:131]
	v_pk_fma_f32 v[148:149], v[148:149], v[146:147], v[130:131] op_sel:[1,0,0] op_sel_hi:[0,1,1]
	s_waitcnt lgkmcnt(3)
	v_pk_fma_f32 v[132:133], v[148:149], v[144:145], v[132:133]
	v_pk_fma_f32 v[148:149], v[148:149], v[146:147], v[132:133] op_sel:[1,0,0] op_sel_hi:[0,1,1]
	s_waitcnt lgkmcnt(2)
	v_pk_fma_f32 v[134:135], v[148:149], v[144:145], v[134:135]
	v_pk_fma_f32 v[148:149], v[148:149], v[146:147], v[134:135] op_sel:[1,0,0] op_sel_hi:[0,1,1]
	s_waitcnt lgkmcnt(1)
	v_pk_fma_f32 v[136:137], v[148:149], v[144:145], v[136:137]
	v_pk_fma_f32 v[148:149], v[148:149], v[146:147], v[136:137] op_sel:[1,0,0] op_sel_hi:[0,1,1]
	s_waitcnt lgkmcnt(0)
	v_pk_fma_f32 v[138:139], v[148:149], v[144:145], v[138:139]
	v_pk_fma_f32 v[148:149], v[148:149], v[146:147], v[138:139] op_sel:[1,0,0] op_sel_hi:[0,1,1]
	v_lshl_add_u32 v65, s2, 9, v116
	ds_write2st64_b32 v65, v148, v149 offset1:1
	v_mov_b32_e32 v65, v112
	v_mov_b32_e32 v91, v113
	v_mov_b32_e32 v63, v115

.LBB0_879:
	s_cmp_eq_u32 s54, 0
	v_add_u32_e32 v90, 32, v76
	v_add_u32_e32 v89, 48, v76
	v_add_u32_e32 v88, 64, v76
	v_add_u32_e32 v87, 0x50, v76
	v_add_u32_e32 v86, 0x60, v76
	v_add_u32_e32 v85, 0x70, v76
	v_add_u32_e32 v84, 0x80, v76
	v_add_u32_e32 v83, 0x90, v76
	v_add_u32_e32 v82, 0xa0, v76
	v_add_u32_e32 v81, 0xb0, v76
	v_add_u32_e32 v80, 0xc0, v76
	v_add_u32_e32 v79, 0xd0, v76
	v_add_u32_e32 v78, 0xe0, v76
	v_add_u32_e32 v77, 0xf0, v76
	s_cbranch_scc1 .LBB0_881
	s_and_b32 s2, s58, 0x400
	v_add_u32_e32 v68, s2, v116
	ds_read2st64_b32 v[94:95], v68 offset1:1
	v_pk_mul_f32 v[96:97], v[58:59], v[66:67]
	v_cndmask_b32_e64 v93, 0, v67, s[88:89]
	v_cndmask_b32_e64 v100, 0, v66, s[88:89]
	v_pk_fma_f32 v[98:99], v[56:57], v[66:67], v[96:97] op_sel:[0,0,1] op_sel_hi:[1,1,0]
	v_pk_fma_f32 v[66:67], v[56:57], v[66:67], v[96:97] op_sel:[0,0,1] op_sel_hi:[1,1,0] neg_lo:[0,0,1] neg_hi:[0,0,1]
	ds_read2st64_b32 v[68:69], v68 offset0:2 offset1:3
	v_mov_b32_e32 v99, v67
	s_waitcnt lgkmcnt(1)
	v_mov_b32_e32 v66, v95
	v_mov_b32_e32 v67, v94
	v_pk_add_f32 v[94:95], v[98:99], v[66:67]
	s_nop 0
	v_pk_mul_f32 v[96:97], v[58:59], v[94:95]
	v_cndmask_b32_e64 v93, v93, v95, s[90:91]
	v_cndmask_b32_e64 v98, v100, v94, s[90:91]
	v_pk_fma_f32 v[66:67], v[56:57], v[94:95], v[96:97] op_sel:[0,0,1] op_sel_hi:[1,1,0]
	v_pk_fma_f32 v[94:95], v[56:57], v[94:95], v[96:97] op_sel:[0,0,1] op_sel_hi:[1,1,0] neg_lo:[0,0,1] neg_hi:[0,0,1]
	v_mul_f32_e32 v96, v109, v98
	v_mov_b32_e32 v67, v95
	ds_read2st64_b32 v[124:125], v76 offset1:1
	ds_read2_b32 v[126:127], v76 offset0:132 offset1:196
	ds_read2st64_b32 v[128:129], v90 offset0:4 offset1:5
	ds_read2st64_b32 v[130:131], v89 offset0:6 offset1:7
	v_mov_b32_e32 v148, v93
	v_mov_b32_e32 v149, v98
	s_waitcnt lgkmcnt(3)
	v_pk_fma_f32 v[124:125], v[148:149], v[144:145], v[124:125]
	v_pk_fma_f32 v[148:149], v[148:149], v[146:147], v[124:125] op_sel:[1,0,0] op_sel_hi:[0,1,1]
	ds_read2st64_b32 v[124:125], v88 offset0:8 offset1:9
	v_cvt_pk_bf16_f32 v94, v148, s0
	ds_write_b16 v73, v94
	v_cvt_pk_bf16_f32 v95, v149, s0
	ds_write_b16 v73, v95 offset:128
	s_waitcnt lgkmcnt(5)
	v_pk_fma_f32 v[126:127], v[148:149], v[144:145], v[126:127]
	v_pk_fma_f32 v[148:149], v[148:149], v[146:147], v[126:127] op_sel:[1,0,0] op_sel_hi:[0,1,1]
	ds_read2st64_b32 v[126:127], v87 offset0:10 offset1:11
	v_cvt_pk_bf16_f32 v94, v148, s0
	ds_write_b16 v73, v94 offset:272
	v_cvt_pk_bf16_f32 v95, v149, s0
	ds_write_b16 v73, v95 offset:400
	s_waitcnt lgkmcnt(7)
	v_pk_fma_f32 v[128:129], v[148:149], v[144:145], v[128:129]
	v_pk_fma_f32 v[148:149], v[148:149], v[146:147], v[128:129] op_sel:[1,0,0] op_sel_hi:[0,1,1]
	ds_read2st64_b32 v[128:129], v86 offset0:12 offset1:13
	v_cvt_pk_bf16_f32 v94, v148, s0
	ds_write_b16 v73, v94 offset:544
	v_cvt_pk_bf16_f32 v95, v149, s0
	ds_write_b16 v73, v95 offset:672
	s_waitcnt lgkmcnt(9)
	v_pk_fma_f32 v[130:131], v[148:149], v[144:145], v[130:131]
	v_pk_fma_f32 v[148:149], v[148:149], v[146:147], v[130:131] op_sel:[1,0,0] op_sel_hi:[0,1,1]
	ds_read2st64_b32 v[130:131], v85 offset0:14 offset1:15
	v_cvt_pk_bf16_f32 v94, v148, s0
	ds_write_b16 v73, v94 offset:816
	v_cvt_pk_bf16_f32 v95, v149, s0
	ds_write_b16 v73, v95 offset:944
	s_waitcnt lgkmcnt(11)
	v_pk_fma_f32 v[124:125], v[148:149], v[144:145], v[124:125]
	v_pk_fma_f32 v[148:149], v[148:149], v[146:147], v[124:125] op_sel:[1,0,0] op_sel_hi:[0,1,1]
	ds_read2st64_b32 v[124:125], v84 offset0:16 offset1:17
	v_cvt_pk_bf16_f32 v94, v148, s0
	ds_write_b16 v73, v94 offset:1088
	v_cvt_pk_bf16_f32 v95, v149, s0
	ds_write_b16 v73, v95 offset:1216
	s_waitcnt lgkmcnt(11)
	v_pk_fma_f32 v[126:127], v[148:149], v[144:145], v[126:127]
	v_pk_fma_f32 v[148:149], v[148:149], v[146:147], v[126:127] op_sel:[1,0,0] op_sel_hi:[0,1,1]
	ds_read2st64_b32 v[126:127], v83 offset0:18 offset1:19
	v_cvt_pk_bf16_f32 v94, v148, s0
	ds_write_b16 v73, v94 offset:1360
	v_cvt_pk_bf16_f32 v95, v149, s0
	ds_write_b16 v73, v95 offset:1488
	s_waitcnt lgkmcnt(11)
	v_pk_fma_f32 v[128:129], v[148:149], v[144:145], v[128:129]
	v_pk_fma_f32 v[148:149], v[148:149], v[146:147], v[128:129] op_sel:[1,0,0] op_sel_hi:[0,1,1]
	ds_read2st64_b32 v[128:129], v82 offset0:20 offset1:21
	v_cvt_pk_bf16_f32 v94, v148, s0
	ds_write_b16 v73, v94 offset:1632
	v_cvt_pk_bf16_f32 v95, v149, s0
	ds_write_b16 v73, v95 offset:1760
	s_waitcnt lgkmcnt(11)
	v_pk_fma_f32 v[130:131], v[148:149], v[144:145], v[130:131]
	v_pk_fma_f32 v[148:149], v[148:149], v[146:147], v[130:131] op_sel:[1,0,0] op_sel_hi:[0,1,1]
	ds_read2st64_b32 v[130:131], v81 offset0:22 offset1:23
	v_cvt_pk_bf16_f32 v94, v148, s0
	ds_write_b16 v73, v94 offset:1904
	v_cvt_pk_bf16_f32 v95, v149, s0
	ds_write_b16 v73, v95 offset:2032
	s_waitcnt lgkmcnt(11)
	v_pk_fma_f32 v[124:125], v[148:149], v[144:145], v[124:125]
	v_pk_fma_f32 v[148:149], v[148:149], v[146:147], v[124:125] op_sel:[1,0,0] op_sel_hi:[0,1,1]
	ds_read2st64_b32 v[124:125], v80 offset0:24 offset1:25
	v_cvt_pk_bf16_f32 v94, v148, s0
	ds_write_b16 v73, v94 offset:2176
	v_cvt_pk_bf16_f32 v95, v149, s0
	ds_write_b16 v73, v95 offset:2304
	s_waitcnt lgkmcnt(11)
	v_pk_fma_f32 v[126:127], v[148:149], v[144:145], v[126:127]
	v_pk_fma_f32 v[148:149], v[148:149], v[146:147], v[126:127] op_sel:[1,0,0] op_sel_hi:[0,1,1]
	ds_read2st64_b32 v[126:127], v79 offset0:26 offset1:27
	v_cvt_pk_bf16_f32 v94, v148, s0
	ds_write_b16 v73, v94 offset:2448
	v_cvt_pk_bf16_f32 v95, v149, s0
	ds_write_b16 v73, v95 offset:2576
	s_waitcnt lgkmcnt(11)
	v_pk_fma_f32 v[128:129], v[148:149], v[144:145], v[128:129]
	v_pk_fma_f32 v[148:149], v[148:149], v[146:147], v[128:129] op_sel:[1,0,0] op_sel_hi:[0,1,1]
	ds_read2st64_b32 v[128:129], v78 offset0:28 offset1:29
	v_cvt_pk_bf16_f32 v94, v148, s0
	ds_write_b16 v73, v94 offset:2720
	v_cvt_pk_bf16_f32 v95, v149, s0
	ds_write_b16 v73, v95 offset:2848
	s_waitcnt lgkmcnt(11)
	v_pk_fma_f32 v[130:131], v[148:149], v[144:145], v[130:131]
	v_pk_fma_f32 v[148:149], v[148:149], v[146:147], v[130:131] op_sel:[1,0,0] op_sel_hi:[0,1,1]
	ds_read2st64_b32 v[130:131], v77 offset0:30 offset1:31
	v_cvt_pk_bf16_f32 v94, v148, s0
	ds_write_b16 v73, v94 offset:2992
	v_cvt_pk_bf16_f32 v95, v149, s0
	ds_write_b16 v73, v95 offset:3120
	s_waitcnt lgkmcnt(11)
	v_pk_fma_f32 v[124:125], v[148:149], v[144:145], v[124:125]
	v_pk_fma_f32 v[148:149], v[148:149], v[146:147], v[124:125] op_sel:[1,0,0] op_sel_hi:[0,1,1]
	v_cvt_pk_bf16_f32 v94, v148, s0
	ds_write_b16 v73, v94 offset:3264
	v_cvt_pk_bf16_f32 v95, v149, s0
	ds_write_b16 v73, v95 offset:3392
	s_waitcnt lgkmcnt(10)
	v_pk_fma_f32 v[126:127], v[148:149], v[144:145], v[126:127]
	v_pk_fma_f32 v[148:149], v[148:149], v[146:147], v[126:127] op_sel:[1,0,0] op_sel_hi:[0,1,1]
	v_cvt_pk_bf16_f32 v94, v148, s0
	ds_write_b16 v73, v94 offset:3536
	v_cvt_pk_bf16_f32 v95, v149, s0
	ds_write_b16 v73, v95 offset:3664
	s_waitcnt lgkmcnt(9)
	v_pk_fma_f32 v[128:129], v[148:149], v[144:145], v[128:129]
	v_pk_fma_f32 v[148:149], v[148:149], v[146:147], v[128:129] op_sel:[1,0,0] op_sel_hi:[0,1,1]
	v_cvt_pk_bf16_f32 v94, v148, s0
	ds_write_b16 v73, v94 offset:3808
	v_cvt_pk_bf16_f32 v95, v149, s0
	ds_write_b16 v73, v95 offset:3936
	s_waitcnt lgkmcnt(8)
	v_pk_fma_f32 v[130:131], v[148:149], v[144:145], v[130:131]
	v_pk_fma_f32 v[148:149], v[148:149], v[146:147], v[130:131] op_sel:[1,0,0] op_sel_hi:[0,1,1]
	v_cvt_pk_bf16_f32 v94, v148, s0
	ds_write_b16 v73, v94 offset:4080
	v_cvt_pk_bf16_f32 v95, v149, s0
	ds_write_b16 v73, v95 offset:4208
	v_mov_b32_e32 v94, v69
	v_mov_b32_e32 v95, v68
	v_pk_add_f32 v[66:67], v[94:95], v[66:67]
	s_waitcnt lgkmcnt(0)
	ds_read_b128 v[94:97], v74
	ds_read_b128 v[98:101], v74 offset:64
	s_waitcnt lgkmcnt(1)
	v_mfma_f32_16x16x32_bf16 v[94:97], v[94:97], v[10:13], 0
	v_add_u32_e32 v93, s54, v72
	v_add_u32_e32 v68, 0xffffff80, v93
	v_ashrrev_i32_e32 v69, 31, v68
	s_waitcnt lgkmcnt(0)
	v_mfma_f32_16x16x32_bf16 v[94:97], v[98:101], v[14:17], v[94:97]
	ds_read_b128 v[98:101], v74 offset:128
	v_lshlrev_b64 v[68:69], 11, v[68:69]
	v_lshl_add_u64 v[68:69], v[60:61], 0, v[68:69]
	s_waitcnt lgkmcnt(0)
	v_mfma_f32_16x16x32_bf16 v[94:97], v[98:101], v[18:21], v[94:97]
	ds_read_b128 v[98:101], v74 offset:192
	s_waitcnt lgkmcnt(0)
	v_mfma_f32_16x16x32_bf16 v[94:97], v[98:101], v[22:25], v[94:97]
	v_lshlrev_b32_e32 v98, 16, v65
	s_nop 6
	v_fma_f32 v94, v110, v98, v94
	v_mul_f32_e32 v99, 0x3d372713, v94
	v_mul_f32_e32 v99, v94, v99
	v_mul_f32_e32 v98, 0.5, v94
	v_fmac_f32_e32 v94, v94, v99
	v_mul_f32_e32 v94, 0x3f4c422a, v94
	v_add_f32_e32 v94, v94, v94
	v_mul_f32_e32 v94, 0x3fb8aa3b, v94
	v_exp_f32_e32 v94, v94
	s_nop 0
	v_add_f32_e32 v94, 1.0, v94
	v_rcp_f32_e32 v94, v94
	s_nop 0
	v_fma_f32 v94, v94, -2.0, 1.0
	v_add_f32_e32 v94, 1.0, v94
	v_mul_f32_e32 v94, v98, v94
	v_cvt_pk_bf16_f32 v94, v94, s0
	global_store_short v[68:69], v94, off
	v_lshlrev_b32_e32 v94, 16, v91
	v_fma_f32 v94, v110, v94, v95
	v_mul_f32_e32 v98, 0x3d372713, v94
	v_mul_f32_e32 v98, v94, v98
	v_mul_f32_e32 v95, 0.5, v94
	v_fmac_f32_e32 v94, v94, v98
	v_mul_f32_e32 v94, 0x3f4c422a, v94
	v_add_f32_e32 v94, v94, v94
	v_mul_f32_e32 v94, 0x3fb8aa3b, v94
	v_exp_f32_e32 v94, v94
	v_add_u32_e32 v68, 0xffffff81, v93
	v_ashrrev_i32_e32 v69, 31, v68
	v_lshlrev_b64 v[68:69], 11, v[68:69]
	v_add_f32_e32 v94, 1.0, v94
	v_rcp_f32_e32 v94, v94
	v_lshl_add_u64 v[68:69], v[60:61], 0, v[68:69]
	v_fma_f32 v94, v94, -2.0, 1.0
	v_add_f32_e32 v94, 1.0, v94
	v_mul_f32_e32 v94, v95, v94
	v_cvt_pk_bf16_f32 v94, v94, s0
	global_store_short v[68:69], v94, off
	v_lshlrev_b32_e32 v94, 16, v92
	v_fma_f32 v94, v110, v94, v96
	v_mul_f32_e32 v96, 0x3d372713, v94
	v_mul_f32_e32 v96, v94, v96
	v_mul_f32_e32 v95, 0.5, v94
	v_fmac_f32_e32 v94, v94, v96
	v_mul_f32_e32 v94, 0x3f4c422a, v94
	v_add_f32_e32 v94, v94, v94
	v_mul_f32_e32 v94, 0x3fb8aa3b, v94
	v_exp_f32_e32 v94, v94
	v_add_u32_e32 v68, 0xffffff82, v93
	v_ashrrev_i32_e32 v69, 31, v68
	v_lshlrev_b64 v[68:69], 11, v[68:69]
	v_add_f32_e32 v94, 1.0, v94
	v_rcp_f32_e32 v94, v94
	v_lshl_add_u64 v[68:69], v[60:61], 0, v[68:69]
	v_fma_f32 v94, v94, -2.0, 1.0
	v_add_f32_e32 v94, 1.0, v94
	v_mul_f32_e32 v94, v95, v94
	v_cvt_pk_bf16_f32 v94, v94, s0
	global_store_short v[68:69], v94, off
	v_add_u32_e32 v68, 0xffffff83, v93
	v_lshlrev_b32_e32 v93, 16, v63
	v_fmac_f32_e32 v97, v110, v93
	v_mul_f32_e32 v94, 0x3d372713, v97
	v_mul_f32_e32 v94, v97, v94
	v_mul_f32_e32 v93, 0.5, v97
	v_fmac_f32_e32 v97, v97, v94
	v_mul_f32_e32 v94, 0x3f4c422a, v97
	v_add_f32_e32 v94, v94, v94
	v_mul_f32_e32 v94, 0x3fb8aa3b, v94
	v_exp_f32_e32 v94, v94
	v_ashrrev_i32_e32 v69, 31, v68
	v_lshlrev_b64 v[68:69], 11, v[68:69]
	v_lshl_add_u64 v[68:69], v[60:61], 0, v[68:69]
	v_add_f32_e32 v94, 1.0, v94
	v_rcp_f32_e32 v94, v94
	s_nop 0
	v_fma_f32 v94, v94, -2.0, 1.0
	v_add_f32_e32 v94, 1.0, v94
	v_mul_f32_e32 v93, v93, v94
	v_cvt_pk_bf16_f32 v93, v93, s0
	global_store_short v[68:69], v93, off
	s_waitcnt lgkmcnt(0)

.LBB0_906:
	s_cmp_eq_u32 s0, -1
	s_cbranch_scc1 .LBB0_905
	s_and_b32 s1, s0, 1
	s_mul_i32 s2, s1, 0xa000
	v_or_b32_e32 v0, s2, v10
	s_nop 0
	v_add_u32_e32 v5, 0, v0
	v_lshl_or_b32 v0, s1, 11, v13
	s_nop 0
	v_add_u32_e32 v14, 0, v0
	v_mov_b32_e32 v0, v11
	v_add_u32_e32 v0, 0, v0
	ds_read_b128 v[48:51], v5 offset:24576
	ds_read_b128 v[40:43], v5 offset:8192
	ds_read_b32 v56, v14
	ds_read_b128 v[44:47], v5 offset:16384
	ds_read_b128 v[52:55], v5 offset:32768
	ds_read_b128 v[112:115], v5
	ds_read_b128 v[68:71], v5 offset:24832
	ds_read_b128 v[60:63], v5 offset:8448
	ds_read_b32 v76, v14 offset:64
	ds_read_b128 v[64:67], v5 offset:16640
	ds_read_b128 v[72:75], v5 offset:33024
	ds_read_b128 v[116:119], v5 offset:256
	s_waitcnt lgkmcnt(6)
	v_pk_mul_f32 v[32:33], v[40:41], v[56:57] op_sel_hi:[1,0]
	v_pk_mul_f32 v[34:35], v[42:43], v[56:57] op_sel_hi:[1,0]
	v_pk_mul_f32 v[20:21], v[48:49], v[8:9]
	v_pk_fma_f32 v[20:21], v[6:7], v[50:51], v[20:21]
	ds_read_b128 v[100:103], v5 offset:25088
	ds_read_b128 v[92:95], v5 offset:8704
	ds_read_b32 v108, v14 offset:128
	ds_read_b128 v[96:99], v5 offset:16896
	ds_read_b128 v[104:107], v5 offset:33280
	ds_read_b128 v[120:123], v5 offset:512
	v_add_f32_e32 v15, v20, v21
	v_pk_fma_f32 v[16:17], v[8:9], v[44:45], v[32:33]
	v_pk_fma_f32 v[18:19], v[6:7], v[46:47], v[34:35]
	v_add_f32_dpp v15, v15, v15 quad_perm:[1,0,3,2] row_mask:0xf bank_mask:0xf bound_ctrl:1
	s_nop 1
	v_add_f32_dpp v15, v15, v15 quad_perm:[2,3,0,1] row_mask:0xf bank_mask:0xf bound_ctrl:1
	s_nop 1
	v_add_f32_dpp v15, v15, v15 row_ror:4 row_mask:0xf bank_mask:0xf bound_ctrl:1
	s_waitcnt lgkmcnt(6)
	v_pk_mul_f32 v[36:37], v[60:61], v[76:77] op_sel_hi:[1,0]
	v_pk_mul_f32 v[38:39], v[62:63], v[76:77] op_sel_hi:[1,0]
	v_add_f32_dpp v22, v15, v15 row_ror:8 row_mask:0xf bank_mask:0xf bound_ctrl:1
	v_pk_fma_f32 v[8:9], v[52:53], v[22:23], v[16:17] op_sel_hi:[1,0,1]
	v_pk_fma_f32 v[6:7], v[54:55], v[22:23], v[18:19] op_sel_hi:[1,0,1]
	v_pk_mul_f32 v[20:21], v[68:69], v[8:9]
	v_pk_fma_f32 v[20:21], v[6:7], v[70:71], v[20:21]
	ds_read_b128 v[48:51], v5 offset:25344
	ds_read_b128 v[40:43], v5 offset:8960
	ds_read_b32 v56, v14 offset:192
	ds_read_b128 v[44:47], v5 offset:17152
	ds_read_b128 v[52:55], v5 offset:33536
	ds_read_b128 v[124:127], v5 offset:768
	s_nop 0
	s_nop 0
	v_add_f32_e32 v15, v20, v21
	v_pk_fma_f32 v[16:17], v[8:9], v[64:65], v[36:37]
	v_pk_fma_f32 v[18:19], v[6:7], v[66:67], v[38:39]
	v_add_f32_dpp v15, v15, v15 quad_perm:[1,0,3,2] row_mask:0xf bank_mask:0xf bound_ctrl:1
	v_pk_mul_f32 v[24:25], v[112:113], v[8:9]
	v_pk_fma_f32 v[24:25], v[6:7], v[114:115], v[24:25]
	v_add_f32_dpp v15, v15, v15 quad_perm:[2,3,0,1] row_mask:0xf bank_mask:0xf bound_ctrl:1
	v_add_f32_e32 v26, v24, v25
	ds_write_b32 v0, v26
	v_add_f32_dpp v15, v15, v15 row_ror:4 row_mask:0xf bank_mask:0xf bound_ctrl:1
	s_waitcnt lgkmcnt(7)
	v_pk_mul_f32 v[32:33], v[92:93], v[108:109] op_sel_hi:[1,0]
	v_pk_mul_f32 v[34:35], v[94:95], v[108:109] op_sel_hi:[1,0]
	v_add_f32_dpp v22, v15, v15 row_ror:8 row_mask:0xf bank_mask:0xf bound_ctrl:1
	v_pk_fma_f32 v[8:9], v[72:73], v[22:23], v[16:17] op_sel_hi:[1,0,1]
	v_pk_fma_f32 v[6:7], v[74:75], v[22:23], v[18:19] op_sel_hi:[1,0,1]
	v_pk_mul_f32 v[20:21], v[100:101], v[8:9]
	v_pk_fma_f32 v[20:21], v[6:7], v[102:103], v[20:21]
	ds_read_b128 v[68:71], v5 offset:25600
	ds_read_b128 v[60:63], v5 offset:9216
	ds_read_b32 v76, v14 offset:256
	ds_read_b128 v[64:67], v5 offset:17408
	ds_read_b128 v[72:75], v5 offset:33792
	ds_read_b128 v[112:115], v5 offset:1024
	s_nop 0
	s_nop 0
	v_add_f32_e32 v15, v20, v21
	v_pk_fma_f32 v[16:17], v[8:9], v[96:97], v[32:33]
	v_pk_fma_f32 v[18:19], v[6:7], v[98:99], v[34:35]
	v_add_f32_dpp v15, v15, v15 quad_perm:[1,0,3,2] row_mask:0xf bank_mask:0xf bound_ctrl:1
	v_pk_mul_f32 v[24:25], v[116:117], v[8:9]
	v_pk_fma_f32 v[24:25], v[6:7], v[118:119], v[24:25]
	v_add_f32_dpp v15, v15, v15 quad_perm:[2,3,0,1] row_mask:0xf bank_mask:0xf bound_ctrl:1
	v_add_f32_e32 v26, v24, v25
	ds_write_b32 v0, v26 offset:256
	v_add_f32_dpp v15, v15, v15 row_ror:4 row_mask:0xf bank_mask:0xf bound_ctrl:1
	s_waitcnt lgkmcnt(8)
	v_pk_mul_f32 v[36:37], v[40:41], v[56:57] op_sel_hi:[1,0]
	v_pk_mul_f32 v[38:39], v[42:43], v[56:57] op_sel_hi:[1,0]
	v_add_f32_dpp v22, v15, v15 row_ror:8 row_mask:0xf bank_mask:0xf bound_ctrl:1
	v_pk_fma_f32 v[8:9], v[104:105], v[22:23], v[16:17] op_sel_hi:[1,0,1]
	v_pk_fma_f32 v[6:7], v[106:107], v[22:23], v[18:19] op_sel_hi:[1,0,1]
	v_pk_mul_f32 v[20:21], v[48:49], v[8:9]
	v_pk_fma_f32 v[20:21], v[6:7], v[50:51], v[20:21]
	ds_read_b128 v[100:103], v5 offset:25856
	ds_read_b128 v[92:95], v5 offset:9472
	ds_read_b32 v108, v14 offset:320
	ds_read_b128 v[96:99], v5 offset:17664
	ds_read_b128 v[104:107], v5 offset:34048
	ds_read_b128 v[116:119], v5 offset:1280
	s_nop 0
	s_nop 0
	v_add_f32_e32 v15, v20, v21
	v_pk_fma_f32 v[16:17], v[8:9], v[44:45], v[36:37]
	v_pk_fma_f32 v[18:19], v[6:7], v[46:47], v[38:39]
	v_add_f32_dpp v15, v15, v15 quad_perm:[1,0,3,2] row_mask:0xf bank_mask:0xf bound_ctrl:1
	v_pk_mul_f32 v[24:25], v[120:121], v[8:9]
	v_pk_fma_f32 v[24:25], v[6:7], v[122:123], v[24:25]
	v_add_f32_dpp v15, v15, v15 quad_perm:[2,3,0,1] row_mask:0xf bank_mask:0xf bound_ctrl:1
	v_add_f32_e32 v26, v24, v25
	ds_write_b32 v0, v26 offset:512
	v_add_f32_dpp v15, v15, v15 row_ror:4 row_mask:0xf bank_mask:0xf bound_ctrl:1
	s_waitcnt lgkmcnt(8)
	v_pk_mul_f32 v[32:33], v[60:61], v[76:77] op_sel_hi:[1,0]
	v_pk_mul_f32 v[34:35], v[62:63], v[76:77] op_sel_hi:[1,0]
	v_add_f32_dpp v22, v15, v15 row_ror:8 row_mask:0xf bank_mask:0xf bound_ctrl:1
	v_pk_fma_f32 v[8:9], v[52:53], v[22:23], v[16:17] op_sel_hi:[1,0,1]
	v_pk_fma_f32 v[6:7], v[54:55], v[22:23], v[18:19] op_sel_hi:[1,0,1]
	v_pk_mul_f32 v[20:21], v[68:69], v[8:9]
	v_pk_fma_f32 v[20:21], v[6:7], v[70:71], v[20:21]
	ds_read_b128 v[48:51], v5 offset:26112
	ds_read_b128 v[40:43], v5 offset:9728
	ds_read_b32 v56, v14 offset:384
	ds_read_b128 v[44:47], v5 offset:17920
	ds_read_b128 v[52:55], v5 offset:34304
	ds_read_b128 v[120:123], v5 offset:1536
	s_nop 0
	s_nop 0
	v_add_f32_e32 v15, v20, v21
	v_pk_fma_f32 v[16:17], v[8:9], v[64:65], v[32:33]
	v_pk_fma_f32 v[18:19], v[6:7], v[66:67], v[34:35]
	v_add_f32_dpp v15, v15, v15 quad_perm:[1,0,3,2] row_mask:0xf bank_mask:0xf bound_ctrl:1
	v_pk_mul_f32 v[24:25], v[124:125], v[8:9]
	v_pk_fma_f32 v[24:25], v[6:7], v[126:127], v[24:25]
	v_add_f32_dpp v15, v15, v15 quad_perm:[2,3,0,1] row_mask:0xf bank_mask:0xf bound_ctrl:1
	v_add_f32_e32 v26, v24, v25
	ds_write_b32 v0, v26 offset:768
	v_add_f32_dpp v15, v15, v15 row_ror:4 row_mask:0xf bank_mask:0xf bound_ctrl:1
	s_waitcnt lgkmcnt(8)
	v_pk_mul_f32 v[36:37], v[92:93], v[108:109] op_sel_hi:[1,0]
	v_pk_mul_f32 v[38:39], v[94:95], v[108:109] op_sel_hi:[1,0]
	v_add_f32_dpp v22, v15, v15 row_ror:8 row_mask:0xf bank_mask:0xf bound_ctrl:1
	v_pk_fma_f32 v[8:9], v[72:73], v[22:23], v[16:17] op_sel_hi:[1,0,1]
	v_pk_fma_f32 v[6:7], v[74:75], v[22:23], v[18:19] op_sel_hi:[1,0,1]
	v_pk_mul_f32 v[20:21], v[100:101], v[8:9]
	v_pk_fma_f32 v[20:21], v[6:7], v[102:103], v[20:21]
	ds_read_b128 v[68:71], v5 offset:26368
	ds_read_b128 v[60:63], v5 offset:9984
	ds_read_b32 v76, v14 offset:448
	ds_read_b128 v[64:67], v5 offset:18176
	ds_read_b128 v[72:75], v5 offset:34560
	ds_read_b128 v[124:127], v5 offset:1792
	s_nop 0
	s_nop 0
	v_add_f32_e32 v15, v20, v21
	v_pk_fma_f32 v[16:17], v[8:9], v[96:97], v[36:37]
	v_pk_fma_f32 v[18:19], v[6:7], v[98:99], v[38:39]
	v_add_f32_dpp v15, v15, v15 quad_perm:[1,0,3,2] row_mask:0xf bank_mask:0xf bound_ctrl:1
	v_pk_mul_f32 v[24:25], v[112:113], v[8:9]
	v_pk_fma_f32 v[24:25], v[6:7], v[114:115], v[24:25]
	v_add_f32_dpp v15, v15, v15 quad_perm:[2,3,0,1] row_mask:0xf bank_mask:0xf bound_ctrl:1
	v_add_f32_e32 v26, v24, v25
	ds_write_b32 v0, v26 offset:1024
	v_add_f32_dpp v15, v15, v15 row_ror:4 row_mask:0xf bank_mask:0xf bound_ctrl:1
	s_waitcnt lgkmcnt(8)
	v_pk_mul_f32 v[32:33], v[40:41], v[56:57] op_sel_hi:[1,0]
	v_pk_mul_f32 v[34:35], v[42:43], v[56:57] op_sel_hi:[1,0]
	v_add_f32_dpp v22, v15, v15 row_ror:8 row_mask:0xf bank_mask:0xf bound_ctrl:1
	v_pk_fma_f32 v[8:9], v[104:105], v[22:23], v[16:17] op_sel_hi:[1,0,1]
	v_pk_fma_f32 v[6:7], v[106:107], v[22:23], v[18:19] op_sel_hi:[1,0,1]
	v_pk_mul_f32 v[20:21], v[48:49], v[8:9]
	v_pk_fma_f32 v[20:21], v[6:7], v[50:51], v[20:21]
	ds_read_b128 v[100:103], v5 offset:26624
	ds_read_b128 v[92:95], v5 offset:10240
	ds_read_b32 v108, v14 offset:512
	ds_read_b128 v[96:99], v5 offset:18432
	ds_read_b128 v[104:107], v5 offset:34816
	ds_read_b128 v[112:115], v5 offset:2048
	s_nop 0
	s_nop 0
	v_add_f32_e32 v15, v20, v21
	v_pk_fma_f32 v[16:17], v[8:9], v[44:45], v[32:33]
	v_pk_fma_f32 v[18:19], v[6:7], v[46:47], v[34:35]
	v_add_f32_dpp v15, v15, v15 quad_perm:[1,0,3,2] row_mask:0xf bank_mask:0xf bound_ctrl:1
	v_pk_mul_f32 v[24:25], v[116:117], v[8:9]
	v_pk_fma_f32 v[24:25], v[6:7], v[118:119], v[24:25]
	v_add_f32_dpp v15, v15, v15 quad_perm:[2,3,0,1] row_mask:0xf bank_mask:0xf bound_ctrl:1
	v_add_f32_e32 v26, v24, v25
	ds_write_b32 v0, v26 offset:1280
	v_add_f32_dpp v15, v15, v15 row_ror:4 row_mask:0xf bank_mask:0xf bound_ctrl:1
	s_waitcnt lgkmcnt(8)
	v_pk_mul_f32 v[36:37], v[60:61], v[76:77] op_sel_hi:[1,0]
	v_pk_mul_f32 v[38:39], v[62:63], v[76:77] op_sel_hi:[1,0]
	v_add_f32_dpp v22, v15, v15 row_ror:8 row_mask:0xf bank_mask:0xf bound_ctrl:1
	v_pk_fma_f32 v[8:9], v[52:53], v[22:23], v[16:17] op_sel_hi:[1,0,1]
	v_pk_fma_f32 v[6:7], v[54:55], v[22:23], v[18:19] op_sel_hi:[1,0,1]
	v_pk_mul_f32 v[20:21], v[68:69], v[8:9]
	v_pk_fma_f32 v[20:21], v[6:7], v[70:71], v[20:21]
	ds_read_b128 v[48:51], v5 offset:26880
	ds_read_b128 v[40:43], v5 offset:10496
	ds_read_b32 v56, v14 offset:576
	ds_read_b128 v[44:47], v5 offset:18688
	ds_read_b128 v[52:55], v5 offset:35072
	ds_read_b128 v[116:119], v5 offset:2304
	s_nop 0
	s_nop 0
	v_add_f32_e32 v15, v20, v21
	v_pk_fma_f32 v[16:17], v[8:9], v[64:65], v[36:37]
	v_pk_fma_f32 v[18:19], v[6:7], v[66:67], v[38:39]
	v_add_f32_dpp v15, v15, v15 quad_perm:[1,0,3,2] row_mask:0xf bank_mask:0xf bound_ctrl:1
	v_pk_mul_f32 v[24:25], v[120:121], v[8:9]
	v_pk_fma_f32 v[24:25], v[6:7], v[122:123], v[24:25]
	v_add_f32_dpp v15, v15, v15 quad_perm:[2,3,0,1] row_mask:0xf bank_mask:0xf bound_ctrl:1
	v_add_f32_e32 v26, v24, v25
	ds_write_b32 v0, v26 offset:1536
	v_add_f32_dpp v15, v15, v15 row_ror:4 row_mask:0xf bank_mask:0xf bound_ctrl:1
	s_waitcnt lgkmcnt(8)
	v_pk_mul_f32 v[32:33], v[92:93], v[108:109] op_sel_hi:[1,0]
	v_pk_mul_f32 v[34:35], v[94:95], v[108:109] op_sel_hi:[1,0]
	v_add_f32_dpp v22, v15, v15 row_ror:8 row_mask:0xf bank_mask:0xf bound_ctrl:1
	v_pk_fma_f32 v[8:9], v[72:73], v[22:23], v[16:17] op_sel_hi:[1,0,1]
	v_pk_fma_f32 v[6:7], v[74:75], v[22:23], v[18:19] op_sel_hi:[1,0,1]
	v_pk_mul_f32 v[20:21], v[100:101], v[8:9]
	v_pk_fma_f32 v[20:21], v[6:7], v[102:103], v[20:21]
	ds_read_b128 v[68:71], v5 offset:27136
	ds_read_b128 v[60:63], v5 offset:10752
	ds_read_b32 v76, v14 offset:640
	ds_read_b128 v[64:67], v5 offset:18944
	ds_read_b128 v[72:75], v5 offset:35328
	ds_read_b128 v[120:123], v5 offset:2560
	s_nop 0
	s_nop 0
	v_add_f32_e32 v15, v20, v21
	v_pk_fma_f32 v[16:17], v[8:9], v[96:97], v[32:33]
	v_pk_fma_f32 v[18:19], v[6:7], v[98:99], v[34:35]
	v_add_f32_dpp v15, v15, v15 quad_perm:[1,0,3,2] row_mask:0xf bank_mask:0xf bound_ctrl:1
	v_pk_mul_f32 v[24:25], v[124:125], v[8:9]
	v_pk_fma_f32 v[24:25], v[6:7], v[126:127], v[24:25]
	v_add_f32_dpp v15, v15, v15 quad_perm:[2,3,0,1] row_mask:0xf bank_mask:0xf bound_ctrl:1
	v_add_f32_e32 v26, v24, v25
	ds_write_b32 v0, v26 offset:1792
	v_add_f32_dpp v15, v15, v15 row_ror:4 row_mask:0xf bank_mask:0xf bound_ctrl:1
	s_waitcnt lgkmcnt(8)
	v_pk_mul_f32 v[36:37], v[40:41], v[56:57] op_sel_hi:[1,0]
	v_pk_mul_f32 v[38:39], v[42:43], v[56:57] op_sel_hi:[1,0]
	v_add_f32_dpp v22, v15, v15 row_ror:8 row_mask:0xf bank_mask:0xf bound_ctrl:1
	v_pk_fma_f32 v[8:9], v[104:105], v[22:23], v[16:17] op_sel_hi:[1,0,1]
	v_pk_fma_f32 v[6:7], v[106:107], v[22:23], v[18:19] op_sel_hi:[1,0,1]
	v_pk_mul_f32 v[20:21], v[48:49], v[8:9]
	v_pk_fma_f32 v[20:21], v[6:7], v[50:51], v[20:21]
	ds_read_b128 v[100:103], v5 offset:27392
	ds_read_b128 v[92:95], v5 offset:11008
	ds_read_b32 v108, v14 offset:704
	ds_read_b128 v[96:99], v5 offset:19200
	ds_read_b128 v[104:107], v5 offset:35584
	ds_read_b128 v[124:127], v5 offset:2816
	s_nop 0
	s_nop 0
	v_add_f32_e32 v15, v20, v21
	v_pk_fma_f32 v[16:17], v[8:9], v[44:45], v[36:37]
	v_pk_fma_f32 v[18:19], v[6:7], v[46:47], v[38:39]
	v_add_f32_dpp v15, v15, v15 quad_perm:[1,0,3,2] row_mask:0xf bank_mask:0xf bound_ctrl:1
	v_pk_mul_f32 v[24:25], v[112:113], v[8:9]
	v_pk_fma_f32 v[24:25], v[6:7], v[114:115], v[24:25]
	v_add_f32_dpp v15, v15, v15 quad_perm:[2,3,0,1] row_mask:0xf bank_mask:0xf bound_ctrl:1
	v_add_f32_e32 v26, v24, v25
	ds_write_b32 v0, v26 offset:2048
	v_add_f32_dpp v15, v15, v15 row_ror:4 row_mask:0xf bank_mask:0xf bound_ctrl:1
	s_waitcnt lgkmcnt(8)
	v_pk_mul_f32 v[32:33], v[60:61], v[76:77] op_sel_hi:[1,0]
	v_pk_mul_f32 v[34:35], v[62:63], v[76:77] op_sel_hi:[1,0]
	v_add_f32_dpp v22, v15, v15 row_ror:8 row_mask:0xf bank_mask:0xf bound_ctrl:1
	v_pk_fma_f32 v[8:9], v[52:53], v[22:23], v[16:17] op_sel_hi:[1,0,1]
	v_pk_fma_f32 v[6:7], v[54:55], v[22:23], v[18:19] op_sel_hi:[1,0,1]
	v_pk_mul_f32 v[20:21], v[68:69], v[8:9]
	v_pk_fma_f32 v[20:21], v[6:7], v[70:71], v[20:21]
	ds_read_b128 v[48:51], v5 offset:27648
	ds_read_b128 v[40:43], v5 offset:11264
	ds_read_b32 v56, v14 offset:768
	ds_read_b128 v[44:47], v5 offset:19456
	ds_read_b128 v[52:55], v5 offset:35840
	ds_read_b128 v[112:115], v5 offset:3072
	s_nop 0
	s_nop 0
	v_add_f32_e32 v15, v20, v21
	v_pk_fma_f32 v[16:17], v[8:9], v[64:65], v[32:33]
	v_pk_fma_f32 v[18:19], v[6:7], v[66:67], v[34:35]
	v_add_f32_dpp v15, v15, v15 quad_perm:[1,0,3,2] row_mask:0xf bank_mask:0xf bound_ctrl:1
	v_pk_mul_f32 v[24:25], v[116:117], v[8:9]
	v_pk_fma_f32 v[24:25], v[6:7], v[118:119], v[24:25]
	v_add_f32_dpp v15, v15, v15 quad_perm:[2,3,0,1] row_mask:0xf bank_mask:0xf bound_ctrl:1
	v_add_f32_e32 v26, v24, v25
	ds_write_b32 v0, v26 offset:2304
	v_add_f32_dpp v15, v15, v15 row_ror:4 row_mask:0xf bank_mask:0xf bound_ctrl:1
	s_waitcnt lgkmcnt(8)
	v_pk_mul_f32 v[36:37], v[92:93], v[108:109] op_sel_hi:[1,0]
	v_pk_mul_f32 v[38:39], v[94:95], v[108:109] op_sel_hi:[1,0]
	v_add_f32_dpp v22, v15, v15 row_ror:8 row_mask:0xf bank_mask:0xf bound_ctrl:1
	v_pk_fma_f32 v[8:9], v[72:73], v[22:23], v[16:17] op_sel_hi:[1,0,1]
	v_pk_fma_f32 v[6:7], v[74:75], v[22:23], v[18:19] op_sel_hi:[1,0,1]
	v_pk_mul_f32 v[20:21], v[100:101], v[8:9]
	v_pk_fma_f32 v[20:21], v[6:7], v[102:103], v[20:21]
	ds_read_b128 v[68:71], v5 offset:27904
	ds_read_b128 v[60:63], v5 offset:11520
	ds_read_b32 v76, v14 offset:832
	ds_read_b128 v[64:67], v5 offset:19712
	ds_read_b128 v[72:75], v5 offset:36096
	ds_read_b128 v[116:119], v5 offset:3328
	s_nop 0
	s_nop 0
	v_add_f32_e32 v15, v20, v21
	v_pk_fma_f32 v[16:17], v[8:9], v[96:97], v[36:37]
	v_pk_fma_f32 v[18:19], v[6:7], v[98:99], v[38:39]
	v_add_f32_dpp v15, v15, v15 quad_perm:[1,0,3,2] row_mask:0xf bank_mask:0xf bound_ctrl:1
	v_pk_mul_f32 v[24:25], v[120:121], v[8:9]
	v_pk_fma_f32 v[24:25], v[6:7], v[122:123], v[24:25]
	v_add_f32_dpp v15, v15, v15 quad_perm:[2,3,0,1] row_mask:0xf bank_mask:0xf bound_ctrl:1
	v_add_f32_e32 v26, v24, v25
	ds_write_b32 v0, v26 offset:2560
	v_add_f32_dpp v15, v15, v15 row_ror:4 row_mask:0xf bank_mask:0xf bound_ctrl:1
	s_waitcnt lgkmcnt(8)
	v_pk_mul_f32 v[32:33], v[40:41], v[56:57] op_sel_hi:[1,0]
	v_pk_mul_f32 v[34:35], v[42:43], v[56:57] op_sel_hi:[1,0]
	v_add_f32_dpp v22, v15, v15 row_ror:8 row_mask:0xf bank_mask:0xf bound_ctrl:1
	v_pk_fma_f32 v[8:9], v[104:105], v[22:23], v[16:17] op_sel_hi:[1,0,1]
	v_pk_fma_f32 v[6:7], v[106:107], v[22:23], v[18:19] op_sel_hi:[1,0,1]
	v_pk_mul_f32 v[20:21], v[48:49], v[8:9]
	v_pk_fma_f32 v[20:21], v[6:7], v[50:51], v[20:21]
	ds_read_b128 v[100:103], v5 offset:28160
	ds_read_b128 v[92:95], v5 offset:11776
	ds_read_b32 v108, v14 offset:896
	ds_read_b128 v[96:99], v5 offset:19968
	ds_read_b128 v[104:107], v5 offset:36352
	ds_read_b128 v[120:123], v5 offset:3584
	s_nop 0
	s_nop 0
	v_add_f32_e32 v15, v20, v21
	v_pk_fma_f32 v[16:17], v[8:9], v[44:45], v[32:33]
	v_pk_fma_f32 v[18:19], v[6:7], v[46:47], v[34:35]
	v_add_f32_dpp v15, v15, v15 quad_perm:[1,0,3,2] row_mask:0xf bank_mask:0xf bound_ctrl:1
	v_pk_mul_f32 v[24:25], v[124:125], v[8:9]
	v_pk_fma_f32 v[24:25], v[6:7], v[126:127], v[24:25]
	v_add_f32_dpp v15, v15, v15 quad_perm:[2,3,0,1] row_mask:0xf bank_mask:0xf bound_ctrl:1
	v_add_f32_e32 v26, v24, v25
	ds_write_b32 v0, v26 offset:2816
	v_add_f32_dpp v15, v15, v15 row_ror:4 row_mask:0xf bank_mask:0xf bound_ctrl:1
	s_waitcnt lgkmcnt(8)
	v_pk_mul_f32 v[36:37], v[60:61], v[76:77] op_sel_hi:[1,0]
	v_pk_mul_f32 v[38:39], v[62:63], v[76:77] op_sel_hi:[1,0]
	v_add_f32_dpp v22, v15, v15 row_ror:8 row_mask:0xf bank_mask:0xf bound_ctrl:1
	v_pk_fma_f32 v[8:9], v[52:53], v[22:23], v[16:17] op_sel_hi:[1,0,1]
	v_pk_fma_f32 v[6:7], v[54:55], v[22:23], v[18:19] op_sel_hi:[1,0,1]
	v_pk_mul_f32 v[20:21], v[68:69], v[8:9]
	v_pk_fma_f32 v[20:21], v[6:7], v[70:71], v[20:21]
	ds_read_b128 v[48:51], v5 offset:28416
	ds_read_b128 v[40:43], v5 offset:12032
	ds_read_b32 v56, v14 offset:960
	ds_read_b128 v[44:47], v5 offset:20224
	ds_read_b128 v[52:55], v5 offset:36608
	ds_read_b128 v[124:127], v5 offset:3840
	s_nop 0
	s_nop 0
	v_add_f32_e32 v15, v20, v21
	v_pk_fma_f32 v[16:17], v[8:9], v[64:65], v[36:37]
	v_pk_fma_f32 v[18:19], v[6:7], v[66:67], v[38:39]
	v_add_f32_dpp v15, v15, v15 quad_perm:[1,0,3,2] row_mask:0xf bank_mask:0xf bound_ctrl:1
	v_pk_mul_f32 v[24:25], v[112:113], v[8:9]
	v_pk_fma_f32 v[24:25], v[6:7], v[114:115], v[24:25]
	v_add_f32_dpp v15, v15, v15 quad_perm:[2,3,0,1] row_mask:0xf bank_mask:0xf bound_ctrl:1
	v_add_f32_e32 v26, v24, v25
	ds_write_b32 v0, v26 offset:3072
	v_add_f32_dpp v15, v15, v15 row_ror:4 row_mask:0xf bank_mask:0xf bound_ctrl:1
	s_waitcnt lgkmcnt(8)
	v_pk_mul_f32 v[32:33], v[92:93], v[108:109] op_sel_hi:[1,0]
	v_pk_mul_f32 v[34:35], v[94:95], v[108:109] op_sel_hi:[1,0]
	v_add_f32_dpp v22, v15, v15 row_ror:8 row_mask:0xf bank_mask:0xf bound_ctrl:1
	v_pk_fma_f32 v[8:9], v[72:73], v[22:23], v[16:17] op_sel_hi:[1,0,1]
	v_pk_fma_f32 v[6:7], v[74:75], v[22:23], v[18:19] op_sel_hi:[1,0,1]
	v_pk_mul_f32 v[20:21], v[100:101], v[8:9]
	v_pk_fma_f32 v[20:21], v[6:7], v[102:103], v[20:21]
	ds_read_b128 v[68:71], v5 offset:28672
	ds_read_b128 v[60:63], v5 offset:12288
	ds_read_b32 v76, v14 offset:1024
	ds_read_b128 v[64:67], v5 offset:20480
	ds_read_b128 v[72:75], v5 offset:36864
	ds_read_b128 v[112:115], v5 offset:4096
	s_nop 0
	s_nop 0
	v_add_f32_e32 v15, v20, v21
	v_pk_fma_f32 v[16:17], v[8:9], v[96:97], v[32:33]
	v_pk_fma_f32 v[18:19], v[6:7], v[98:99], v[34:35]
	v_add_f32_dpp v15, v15, v15 quad_perm:[1,0,3,2] row_mask:0xf bank_mask:0xf bound_ctrl:1
	v_pk_mul_f32 v[24:25], v[116:117], v[8:9]
	v_pk_fma_f32 v[24:25], v[6:7], v[118:119], v[24:25]
	v_add_f32_dpp v15, v15, v15 quad_perm:[2,3,0,1] row_mask:0xf bank_mask:0xf bound_ctrl:1
	v_add_f32_e32 v26, v24, v25
	ds_write_b32 v0, v26 offset:3328
	v_add_f32_dpp v15, v15, v15 row_ror:4 row_mask:0xf bank_mask:0xf bound_ctrl:1
	s_waitcnt lgkmcnt(8)
	v_pk_mul_f32 v[36:37], v[40:41], v[56:57] op_sel_hi:[1,0]
	v_pk_mul_f32 v[38:39], v[42:43], v[56:57] op_sel_hi:[1,0]
	v_add_f32_dpp v22, v15, v15 row_ror:8 row_mask:0xf bank_mask:0xf bound_ctrl:1
	v_pk_fma_f32 v[8:9], v[104:105], v[22:23], v[16:17] op_sel_hi:[1,0,1]
	v_pk_fma_f32 v[6:7], v[106:107], v[22:23], v[18:19] op_sel_hi:[1,0,1]
	v_pk_mul_f32 v[20:21], v[48:49], v[8:9]
	v_pk_fma_f32 v[20:21], v[6:7], v[50:51], v[20:21]
	ds_read_b128 v[100:103], v5 offset:28928
	ds_read_b128 v[92:95], v5 offset:12544
	ds_read_b32 v108, v14 offset:1088
	ds_read_b128 v[96:99], v5 offset:20736
	ds_read_b128 v[104:107], v5 offset:37120
	ds_read_b128 v[116:119], v5 offset:4352
	s_nop 0
	s_nop 0
	v_add_f32_e32 v15, v20, v21
	v_pk_fma_f32 v[16:17], v[8:9], v[44:45], v[36:37]
	v_pk_fma_f32 v[18:19], v[6:7], v[46:47], v[38:39]
	v_add_f32_dpp v15, v15, v15 quad_perm:[1,0,3,2] row_mask:0xf bank_mask:0xf bound_ctrl:1
	v_pk_mul_f32 v[24:25], v[120:121], v[8:9]
	v_pk_fma_f32 v[24:25], v[6:7], v[122:123], v[24:25]
	v_add_f32_dpp v15, v15, v15 quad_perm:[2,3,0,1] row_mask:0xf bank_mask:0xf bound_ctrl:1
	v_add_f32_e32 v26, v24, v25
	ds_write_b32 v0, v26 offset:3584
	v_add_f32_dpp v15, v15, v15 row_ror:4 row_mask:0xf bank_mask:0xf bound_ctrl:1
	s_waitcnt lgkmcnt(8)
	v_pk_mul_f32 v[32:33], v[60:61], v[76:77] op_sel_hi:[1,0]
	v_pk_mul_f32 v[34:35], v[62:63], v[76:77] op_sel_hi:[1,0]
	v_add_f32_dpp v22, v15, v15 row_ror:8 row_mask:0xf bank_mask:0xf bound_ctrl:1
	v_pk_fma_f32 v[8:9], v[52:53], v[22:23], v[16:17] op_sel_hi:[1,0,1]
	v_pk_fma_f32 v[6:7], v[54:55], v[22:23], v[18:19] op_sel_hi:[1,0,1]
	v_pk_mul_f32 v[20:21], v[68:69], v[8:9]
	v_pk_fma_f32 v[20:21], v[6:7], v[70:71], v[20:21]
	ds_read_b128 v[48:51], v5 offset:29184
	ds_read_b128 v[40:43], v5 offset:12800
	ds_read_b32 v56, v14 offset:1152
	ds_read_b128 v[44:47], v5 offset:20992
	ds_read_b128 v[52:55], v5 offset:37376
	ds_read_b128 v[120:123], v5 offset:4608
	s_nop 0
	s_nop 0
	v_add_f32_e32 v15, v20, v21
	v_pk_fma_f32 v[16:17], v[8:9], v[64:65], v[32:33]
	v_pk_fma_f32 v[18:19], v[6:7], v[66:67], v[34:35]
	v_add_f32_dpp v15, v15, v15 quad_perm:[1,0,3,2] row_mask:0xf bank_mask:0xf bound_ctrl:1
	v_pk_mul_f32 v[24:25], v[124:125], v[8:9]
	v_pk_fma_f32 v[24:25], v[6:7], v[126:127], v[24:25]
	v_add_f32_dpp v15, v15, v15 quad_perm:[2,3,0,1] row_mask:0xf bank_mask:0xf bound_ctrl:1
	v_add_f32_e32 v26, v24, v25
	ds_write_b32 v0, v26 offset:3840
	v_add_f32_dpp v15, v15, v15 row_ror:4 row_mask:0xf bank_mask:0xf bound_ctrl:1
	s_waitcnt lgkmcnt(8)
	v_pk_mul_f32 v[36:37], v[92:93], v[108:109] op_sel_hi:[1,0]
	v_pk_mul_f32 v[38:39], v[94:95], v[108:109] op_sel_hi:[1,0]
	v_add_f32_dpp v22, v15, v15 row_ror:8 row_mask:0xf bank_mask:0xf bound_ctrl:1
	v_pk_fma_f32 v[8:9], v[72:73], v[22:23], v[16:17] op_sel_hi:[1,0,1]
	v_pk_fma_f32 v[6:7], v[74:75], v[22:23], v[18:19] op_sel_hi:[1,0,1]
	v_pk_mul_f32 v[20:21], v[100:101], v[8:9]
	v_pk_fma_f32 v[20:21], v[6:7], v[102:103], v[20:21]
	ds_read_b128 v[68:71], v5 offset:29440
	ds_read_b128 v[60:63], v5 offset:13056
	ds_read_b32 v76, v14 offset:1216
	ds_read_b128 v[64:67], v5 offset:21248
	ds_read_b128 v[72:75], v5 offset:37632
	ds_read_b128 v[124:127], v5 offset:4864
	s_nop 0
	s_nop 0
	v_add_f32_e32 v15, v20, v21
	v_pk_fma_f32 v[16:17], v[8:9], v[96:97], v[36:37]
	v_pk_fma_f32 v[18:19], v[6:7], v[98:99], v[38:39]
	v_add_f32_dpp v15, v15, v15 quad_perm:[1,0,3,2] row_mask:0xf bank_mask:0xf bound_ctrl:1
	v_pk_mul_f32 v[24:25], v[112:113], v[8:9]
	v_pk_fma_f32 v[24:25], v[6:7], v[114:115], v[24:25]
	v_add_f32_dpp v15, v15, v15 quad_perm:[2,3,0,1] row_mask:0xf bank_mask:0xf bound_ctrl:1
	v_add_f32_e32 v26, v24, v25
	ds_write_b32 v0, v26 offset:4096
	v_add_f32_dpp v15, v15, v15 row_ror:4 row_mask:0xf bank_mask:0xf bound_ctrl:1
	s_waitcnt lgkmcnt(8)
	v_pk_mul_f32 v[32:33], v[40:41], v[56:57] op_sel_hi:[1,0]
	v_pk_mul_f32 v[34:35], v[42:43], v[56:57] op_sel_hi:[1,0]
	v_add_f32_dpp v22, v15, v15 row_ror:8 row_mask:0xf bank_mask:0xf bound_ctrl:1
	v_pk_fma_f32 v[8:9], v[104:105], v[22:23], v[16:17] op_sel_hi:[1,0,1]
	v_pk_fma_f32 v[6:7], v[106:107], v[22:23], v[18:19] op_sel_hi:[1,0,1]
	v_pk_mul_f32 v[20:21], v[48:49], v[8:9]
	v_pk_fma_f32 v[20:21], v[6:7], v[50:51], v[20:21]
	ds_read_b128 v[100:103], v5 offset:29696
	ds_read_b128 v[92:95], v5 offset:13312
	ds_read_b32 v108, v14 offset:1280
	ds_read_b128 v[96:99], v5 offset:21504
	ds_read_b128 v[104:107], v5 offset:37888
	ds_read_b128 v[112:115], v5 offset:5120
	s_nop 0
	s_nop 0
	v_add_f32_e32 v15, v20, v21
	v_pk_fma_f32 v[16:17], v[8:9], v[44:45], v[32:33]
	v_pk_fma_f32 v[18:19], v[6:7], v[46:47], v[34:35]
	v_add_f32_dpp v15, v15, v15 quad_perm:[1,0,3,2] row_mask:0xf bank_mask:0xf bound_ctrl:1
	v_pk_mul_f32 v[24:25], v[116:117], v[8:9]
	v_pk_fma_f32 v[24:25], v[6:7], v[118:119], v[24:25]
	v_add_f32_dpp v15, v15, v15 quad_perm:[2,3,0,1] row_mask:0xf bank_mask:0xf bound_ctrl:1
	v_add_f32_e32 v26, v24, v25
	ds_write_b32 v0, v26 offset:4352
	v_add_f32_dpp v15, v15, v15 row_ror:4 row_mask:0xf bank_mask:0xf bound_ctrl:1
	s_waitcnt lgkmcnt(8)
	v_pk_mul_f32 v[36:37], v[60:61], v[76:77] op_sel_hi:[1,0]
	v_pk_mul_f32 v[38:39], v[62:63], v[76:77] op_sel_hi:[1,0]
	v_add_f32_dpp v22, v15, v15 row_ror:8 row_mask:0xf bank_mask:0xf bound_ctrl:1
	v_pk_fma_f32 v[8:9], v[52:53], v[22:23], v[16:17] op_sel_hi:[1,0,1]
	v_pk_fma_f32 v[6:7], v[54:55], v[22:23], v[18:19] op_sel_hi:[1,0,1]
	v_pk_mul_f32 v[20:21], v[68:69], v[8:9]
	v_pk_fma_f32 v[20:21], v[6:7], v[70:71], v[20:21]
	ds_read_b128 v[48:51], v5 offset:29952
	ds_read_b128 v[40:43], v5 offset:13568
	ds_read_b32 v56, v14 offset:1344
	ds_read_b128 v[44:47], v5 offset:21760
	ds_read_b128 v[52:55], v5 offset:38144
	ds_read_b128 v[116:119], v5 offset:5376
	s_nop 0
	s_nop 0
	v_add_f32_e32 v15, v20, v21
	v_pk_fma_f32 v[16:17], v[8:9], v[64:65], v[36:37]
	v_pk_fma_f32 v[18:19], v[6:7], v[66:67], v[38:39]
	v_add_f32_dpp v15, v15, v15 quad_perm:[1,0,3,2] row_mask:0xf bank_mask:0xf bound_ctrl:1
	v_pk_mul_f32 v[24:25], v[120:121], v[8:9]
	v_pk_fma_f32 v[24:25], v[6:7], v[122:123], v[24:25]
	v_add_f32_dpp v15, v15, v15 quad_perm:[2,3,0,1] row_mask:0xf bank_mask:0xf bound_ctrl:1
	v_add_f32_e32 v26, v24, v25
	ds_write_b32 v0, v26 offset:4608
	v_add_f32_dpp v15, v15, v15 row_ror:4 row_mask:0xf bank_mask:0xf bound_ctrl:1
	s_waitcnt lgkmcnt(8)
	v_pk_mul_f32 v[32:33], v[92:93], v[108:109] op_sel_hi:[1,0]
	v_pk_mul_f32 v[34:35], v[94:95], v[108:109] op_sel_hi:[1,0]
	v_add_f32_dpp v22, v15, v15 row_ror:8 row_mask:0xf bank_mask:0xf bound_ctrl:1
	v_pk_fma_f32 v[8:9], v[72:73], v[22:23], v[16:17] op_sel_hi:[1,0,1]
	v_pk_fma_f32 v[6:7], v[74:75], v[22:23], v[18:19] op_sel_hi:[1,0,1]
	v_pk_mul_f32 v[20:21], v[100:101], v[8:9]
	v_pk_fma_f32 v[20:21], v[6:7], v[102:103], v[20:21]
	ds_read_b128 v[68:71], v5 offset:30208
	ds_read_b128 v[60:63], v5 offset:13824
	ds_read_b32 v76, v14 offset:1408
	ds_read_b128 v[64:67], v5 offset:22016
	ds_read_b128 v[72:75], v5 offset:38400
	ds_read_b128 v[120:123], v5 offset:5632
	s_nop 0
	s_nop 0
	v_add_f32_e32 v15, v20, v21
	v_pk_fma_f32 v[16:17], v[8:9], v[96:97], v[32:33]
	v_pk_fma_f32 v[18:19], v[6:7], v[98:99], v[34:35]
	v_add_f32_dpp v15, v15, v15 quad_perm:[1,0,3,2] row_mask:0xf bank_mask:0xf bound_ctrl:1
	v_pk_mul_f32 v[24:25], v[124:125], v[8:9]
	v_pk_fma_f32 v[24:25], v[6:7], v[126:127], v[24:25]
	v_add_f32_dpp v15, v15, v15 quad_perm:[2,3,0,1] row_mask:0xf bank_mask:0xf bound_ctrl:1
	v_add_f32_e32 v26, v24, v25
	ds_write_b32 v0, v26 offset:4864
	v_add_f32_dpp v15, v15, v15 row_ror:4 row_mask:0xf bank_mask:0xf bound_ctrl:1
	s_waitcnt lgkmcnt(8)
	v_pk_mul_f32 v[36:37], v[40:41], v[56:57] op_sel_hi:[1,0]
	v_pk_mul_f32 v[38:39], v[42:43], v[56:57] op_sel_hi:[1,0]
	v_add_f32_dpp v22, v15, v15 row_ror:8 row_mask:0xf bank_mask:0xf bound_ctrl:1
	v_pk_fma_f32 v[8:9], v[104:105], v[22:23], v[16:17] op_sel_hi:[1,0,1]
	v_pk_fma_f32 v[6:7], v[106:107], v[22:23], v[18:19] op_sel_hi:[1,0,1]
	v_pk_mul_f32 v[20:21], v[48:49], v[8:9]
	v_pk_fma_f32 v[20:21], v[6:7], v[50:51], v[20:21]
	ds_read_b128 v[100:103], v5 offset:30464
	ds_read_b128 v[92:95], v5 offset:14080
	ds_read_b32 v108, v14 offset:1472
	ds_read_b128 v[96:99], v5 offset:22272
	ds_read_b128 v[104:107], v5 offset:38656
	ds_read_b128 v[124:127], v5 offset:5888
	s_nop 0
	s_nop 0
	v_add_f32_e32 v15, v20, v21
	v_pk_fma_f32 v[16:17], v[8:9], v[44:45], v[36:37]
	v_pk_fma_f32 v[18:19], v[6:7], v[46:47], v[38:39]
	v_add_f32_dpp v15, v15, v15 quad_perm:[1,0,3,2] row_mask:0xf bank_mask:0xf bound_ctrl:1
	v_pk_mul_f32 v[24:25], v[112:113], v[8:9]
	v_pk_fma_f32 v[24:25], v[6:7], v[114:115], v[24:25]
	v_add_f32_dpp v15, v15, v15 quad_perm:[2,3,0,1] row_mask:0xf bank_mask:0xf bound_ctrl:1
	v_add_f32_e32 v26, v24, v25
	ds_write_b32 v0, v26 offset:5120
	v_add_f32_dpp v15, v15, v15 row_ror:4 row_mask:0xf bank_mask:0xf bound_ctrl:1
	s_waitcnt lgkmcnt(8)
	v_pk_mul_f32 v[32:33], v[60:61], v[76:77] op_sel_hi:[1,0]
	v_pk_mul_f32 v[34:35], v[62:63], v[76:77] op_sel_hi:[1,0]
	v_add_f32_dpp v22, v15, v15 row_ror:8 row_mask:0xf bank_mask:0xf bound_ctrl:1
	v_pk_fma_f32 v[8:9], v[52:53], v[22:23], v[16:17] op_sel_hi:[1,0,1]
	v_pk_fma_f32 v[6:7], v[54:55], v[22:23], v[18:19] op_sel_hi:[1,0,1]
	v_pk_mul_f32 v[20:21], v[68:69], v[8:9]
	v_pk_fma_f32 v[20:21], v[6:7], v[70:71], v[20:21]
	ds_read_b128 v[48:51], v5 offset:30720
	ds_read_b128 v[40:43], v5 offset:14336
	ds_read_b32 v56, v14 offset:1536
	ds_read_b128 v[44:47], v5 offset:22528
	ds_read_b128 v[52:55], v5 offset:38912
	ds_read_b128 v[112:115], v5 offset:6144
	s_nop 0
	s_nop 0
	v_add_f32_e32 v15, v20, v21
	v_pk_fma_f32 v[16:17], v[8:9], v[64:65], v[32:33]
	v_pk_fma_f32 v[18:19], v[6:7], v[66:67], v[34:35]
	v_add_f32_dpp v15, v15, v15 quad_perm:[1,0,3,2] row_mask:0xf bank_mask:0xf bound_ctrl:1
	v_pk_mul_f32 v[24:25], v[116:117], v[8:9]
	v_pk_fma_f32 v[24:25], v[6:7], v[118:119], v[24:25]
	v_add_f32_dpp v15, v15, v15 quad_perm:[2,3,0,1] row_mask:0xf bank_mask:0xf bound_ctrl:1
	v_add_f32_e32 v26, v24, v25
	ds_write_b32 v0, v26 offset:5376
	v_add_f32_dpp v15, v15, v15 row_ror:4 row_mask:0xf bank_mask:0xf bound_ctrl:1
	s_waitcnt lgkmcnt(8)
	v_pk_mul_f32 v[36:37], v[92:93], v[108:109] op_sel_hi:[1,0]
	v_pk_mul_f32 v[38:39], v[94:95], v[108:109] op_sel_hi:[1,0]
	v_add_f32_dpp v22, v15, v15 row_ror:8 row_mask:0xf bank_mask:0xf bound_ctrl:1
	v_pk_fma_f32 v[8:9], v[72:73], v[22:23], v[16:17] op_sel_hi:[1,0,1]
	v_pk_fma_f32 v[6:7], v[74:75], v[22:23], v[18:19] op_sel_hi:[1,0,1]
	v_pk_mul_f32 v[20:21], v[100:101], v[8:9]
	v_pk_fma_f32 v[20:21], v[6:7], v[102:103], v[20:21]
	ds_read_b128 v[68:71], v5 offset:30976
	ds_read_b128 v[60:63], v5 offset:14592
	ds_read_b32 v76, v14 offset:1600
	ds_read_b128 v[64:67], v5 offset:22784
	ds_read_b128 v[72:75], v5 offset:39168
	ds_read_b128 v[116:119], v5 offset:6400
	s_nop 0
	s_nop 0
	v_add_f32_e32 v15, v20, v21
	v_pk_fma_f32 v[16:17], v[8:9], v[96:97], v[36:37]
	v_pk_fma_f32 v[18:19], v[6:7], v[98:99], v[38:39]
	v_add_f32_dpp v15, v15, v15 quad_perm:[1,0,3,2] row_mask:0xf bank_mask:0xf bound_ctrl:1
	v_pk_mul_f32 v[24:25], v[120:121], v[8:9]
	v_pk_fma_f32 v[24:25], v[6:7], v[122:123], v[24:25]
	v_add_f32_dpp v15, v15, v15 quad_perm:[2,3,0,1] row_mask:0xf bank_mask:0xf bound_ctrl:1
	v_add_f32_e32 v26, v24, v25
	ds_write_b32 v0, v26 offset:5632
	v_add_f32_dpp v15, v15, v15 row_ror:4 row_mask:0xf bank_mask:0xf bound_ctrl:1
	s_waitcnt lgkmcnt(8)
	v_pk_mul_f32 v[32:33], v[40:41], v[56:57] op_sel_hi:[1,0]
	v_pk_mul_f32 v[34:35], v[42:43], v[56:57] op_sel_hi:[1,0]
	v_add_f32_dpp v22, v15, v15 row_ror:8 row_mask:0xf bank_mask:0xf bound_ctrl:1
	v_pk_fma_f32 v[8:9], v[104:105], v[22:23], v[16:17] op_sel_hi:[1,0,1]
	v_pk_fma_f32 v[6:7], v[106:107], v[22:23], v[18:19] op_sel_hi:[1,0,1]
	v_pk_mul_f32 v[20:21], v[48:49], v[8:9]
	v_pk_fma_f32 v[20:21], v[6:7], v[50:51], v[20:21]
	ds_read_b128 v[100:103], v5 offset:31232
	ds_read_b128 v[92:95], v5 offset:14848
	ds_read_b32 v108, v14 offset:1664
	ds_read_b128 v[96:99], v5 offset:23040
	ds_read_b128 v[104:107], v5 offset:39424
	ds_read_b128 v[120:123], v5 offset:6656
	s_nop 0
	s_nop 0
	v_add_f32_e32 v15, v20, v21
	v_pk_fma_f32 v[16:17], v[8:9], v[44:45], v[32:33]
	v_pk_fma_f32 v[18:19], v[6:7], v[46:47], v[34:35]
	v_add_f32_dpp v15, v15, v15 quad_perm:[1,0,3,2] row_mask:0xf bank_mask:0xf bound_ctrl:1
	v_pk_mul_f32 v[24:25], v[124:125], v[8:9]
	v_pk_fma_f32 v[24:25], v[6:7], v[126:127], v[24:25]
	v_add_f32_dpp v15, v15, v15 quad_perm:[2,3,0,1] row_mask:0xf bank_mask:0xf bound_ctrl:1
	v_add_f32_e32 v26, v24, v25
	ds_write_b32 v0, v26 offset:5888
	v_add_f32_dpp v15, v15, v15 row_ror:4 row_mask:0xf bank_mask:0xf bound_ctrl:1
	s_waitcnt lgkmcnt(8)
	v_pk_mul_f32 v[36:37], v[60:61], v[76:77] op_sel_hi:[1,0]
	v_pk_mul_f32 v[38:39], v[62:63], v[76:77] op_sel_hi:[1,0]
	v_add_f32_dpp v22, v15, v15 row_ror:8 row_mask:0xf bank_mask:0xf bound_ctrl:1
	v_pk_fma_f32 v[8:9], v[52:53], v[22:23], v[16:17] op_sel_hi:[1,0,1]
	v_pk_fma_f32 v[6:7], v[54:55], v[22:23], v[18:19] op_sel_hi:[1,0,1]
	v_pk_mul_f32 v[20:21], v[68:69], v[8:9]
	v_pk_fma_f32 v[20:21], v[6:7], v[70:71], v[20:21]
	ds_read_b128 v[48:51], v5 offset:31488
	ds_read_b128 v[40:43], v5 offset:15104
	ds_read_b32 v56, v14 offset:1728
	ds_read_b128 v[44:47], v5 offset:23296
	ds_read_b128 v[52:55], v5 offset:39680
	ds_read_b128 v[124:127], v5 offset:6912
	s_nop 0
	s_nop 0
	v_add_f32_e32 v15, v20, v21
	v_pk_fma_f32 v[16:17], v[8:9], v[64:65], v[36:37]
	v_pk_fma_f32 v[18:19], v[6:7], v[66:67], v[38:39]
	v_add_f32_dpp v15, v15, v15 quad_perm:[1,0,3,2] row_mask:0xf bank_mask:0xf bound_ctrl:1
	v_pk_mul_f32 v[24:25], v[112:113], v[8:9]
	v_pk_fma_f32 v[24:25], v[6:7], v[114:115], v[24:25]
	v_add_f32_dpp v15, v15, v15 quad_perm:[2,3,0,1] row_mask:0xf bank_mask:0xf bound_ctrl:1
	v_add_f32_e32 v26, v24, v25
	ds_write_b32 v0, v26 offset:6144
	v_add_f32_dpp v15, v15, v15 row_ror:4 row_mask:0xf bank_mask:0xf bound_ctrl:1
	s_waitcnt lgkmcnt(8)
	v_pk_mul_f32 v[32:33], v[92:93], v[108:109] op_sel_hi:[1,0]
	v_pk_mul_f32 v[34:35], v[94:95], v[108:109] op_sel_hi:[1,0]
	v_add_f32_dpp v22, v15, v15 row_ror:8 row_mask:0xf bank_mask:0xf bound_ctrl:1
	v_pk_fma_f32 v[8:9], v[72:73], v[22:23], v[16:17] op_sel_hi:[1,0,1]
	v_pk_fma_f32 v[6:7], v[74:75], v[22:23], v[18:19] op_sel_hi:[1,0,1]
	v_pk_mul_f32 v[20:21], v[100:101], v[8:9]
	v_pk_fma_f32 v[20:21], v[6:7], v[102:103], v[20:21]
	ds_read_b128 v[68:71], v5 offset:31744
	ds_read_b128 v[60:63], v5 offset:15360
	ds_read_b32 v76, v14 offset:1792
	ds_read_b128 v[64:67], v5 offset:23552
	ds_read_b128 v[72:75], v5 offset:39936
	ds_read_b128 v[112:115], v5 offset:7168
	s_nop 0
	s_nop 0
	v_add_f32_e32 v15, v20, v21
	v_pk_fma_f32 v[16:17], v[8:9], v[96:97], v[32:33]
	v_pk_fma_f32 v[18:19], v[6:7], v[98:99], v[34:35]
	v_add_f32_dpp v15, v15, v15 quad_perm:[1,0,3,2] row_mask:0xf bank_mask:0xf bound_ctrl:1
	v_pk_mul_f32 v[24:25], v[116:117], v[8:9]
	v_pk_fma_f32 v[24:25], v[6:7], v[118:119], v[24:25]
	v_add_f32_dpp v15, v15, v15 quad_perm:[2,3,0,1] row_mask:0xf bank_mask:0xf bound_ctrl:1
	v_add_f32_e32 v26, v24, v25
	ds_write_b32 v0, v26 offset:6400
	v_add_f32_dpp v15, v15, v15 row_ror:4 row_mask:0xf bank_mask:0xf bound_ctrl:1
	s_waitcnt lgkmcnt(8)
	v_pk_mul_f32 v[36:37], v[40:41], v[56:57] op_sel_hi:[1,0]
	v_pk_mul_f32 v[38:39], v[42:43], v[56:57] op_sel_hi:[1,0]
	v_add_f32_dpp v22, v15, v15 row_ror:8 row_mask:0xf bank_mask:0xf bound_ctrl:1
	v_pk_fma_f32 v[8:9], v[104:105], v[22:23], v[16:17] op_sel_hi:[1,0,1]
	v_pk_fma_f32 v[6:7], v[106:107], v[22:23], v[18:19] op_sel_hi:[1,0,1]
	v_pk_mul_f32 v[20:21], v[48:49], v[8:9]
	v_pk_fma_f32 v[20:21], v[6:7], v[50:51], v[20:21]
	ds_read_b128 v[100:103], v5 offset:32000
	ds_read_b128 v[92:95], v5 offset:15616
	ds_read_b32 v108, v14 offset:1856
	ds_read_b128 v[96:99], v5 offset:23808
	ds_read_b128 v[104:107], v5 offset:40192
	ds_read_b128 v[116:119], v5 offset:7424
	s_nop 0
	s_nop 0
	v_add_f32_e32 v15, v20, v21
	v_pk_fma_f32 v[16:17], v[8:9], v[44:45], v[36:37]
	v_pk_fma_f32 v[18:19], v[6:7], v[46:47], v[38:39]
	v_add_f32_dpp v15, v15, v15 quad_perm:[1,0,3,2] row_mask:0xf bank_mask:0xf bound_ctrl:1
	v_pk_mul_f32 v[24:25], v[120:121], v[8:9]
	v_pk_fma_f32 v[24:25], v[6:7], v[122:123], v[24:25]
	v_add_f32_dpp v15, v15, v15 quad_perm:[2,3,0,1] row_mask:0xf bank_mask:0xf bound_ctrl:1
	v_add_f32_e32 v26, v24, v25
	ds_write_b32 v0, v26 offset:6656
	v_add_f32_dpp v15, v15, v15 row_ror:4 row_mask:0xf bank_mask:0xf bound_ctrl:1
	s_waitcnt lgkmcnt(8)
	v_pk_mul_f32 v[32:33], v[60:61], v[76:77] op_sel_hi:[1,0]
	v_pk_mul_f32 v[34:35], v[62:63], v[76:77] op_sel_hi:[1,0]
	v_add_f32_dpp v22, v15, v15 row_ror:8 row_mask:0xf bank_mask:0xf bound_ctrl:1
	v_pk_fma_f32 v[8:9], v[52:53], v[22:23], v[16:17] op_sel_hi:[1,0,1]
	v_pk_fma_f32 v[6:7], v[54:55], v[22:23], v[18:19] op_sel_hi:[1,0,1]
	v_pk_mul_f32 v[20:21], v[68:69], v[8:9]
	v_pk_fma_f32 v[20:21], v[6:7], v[70:71], v[20:21]
	ds_read_b128 v[48:51], v5 offset:32256
	ds_read_b128 v[40:43], v5 offset:15872
	ds_read_b32 v56, v14 offset:1920
	ds_read_b128 v[44:47], v5 offset:24064
	ds_read_b128 v[52:55], v5 offset:40448
	ds_read_b128 v[120:123], v5 offset:7680
	s_nop 0
	s_nop 0
	v_add_f32_e32 v15, v20, v21
	v_pk_fma_f32 v[16:17], v[8:9], v[64:65], v[32:33]
	v_pk_fma_f32 v[18:19], v[6:7], v[66:67], v[34:35]
	v_add_f32_dpp v15, v15, v15 quad_perm:[1,0,3,2] row_mask:0xf bank_mask:0xf bound_ctrl:1
	v_pk_mul_f32 v[24:25], v[124:125], v[8:9]
	v_pk_fma_f32 v[24:25], v[6:7], v[126:127], v[24:25]
	v_add_f32_dpp v15, v15, v15 quad_perm:[2,3,0,1] row_mask:0xf bank_mask:0xf bound_ctrl:1
	v_add_f32_e32 v26, v24, v25
	ds_write_b32 v0, v26 offset:6912
	v_add_f32_dpp v15, v15, v15 row_ror:4 row_mask:0xf bank_mask:0xf bound_ctrl:1
	s_waitcnt lgkmcnt(8)
	v_pk_mul_f32 v[36:37], v[92:93], v[108:109] op_sel_hi:[1,0]
	v_pk_mul_f32 v[38:39], v[94:95], v[108:109] op_sel_hi:[1,0]
	v_add_f32_dpp v22, v15, v15 row_ror:8 row_mask:0xf bank_mask:0xf bound_ctrl:1
	v_pk_fma_f32 v[8:9], v[72:73], v[22:23], v[16:17] op_sel_hi:[1,0,1]
	v_pk_fma_f32 v[6:7], v[74:75], v[22:23], v[18:19] op_sel_hi:[1,0,1]
	v_pk_mul_f32 v[20:21], v[100:101], v[8:9]
	v_pk_fma_f32 v[20:21], v[6:7], v[102:103], v[20:21]
	ds_read_b128 v[68:71], v5 offset:32512
	ds_read_b128 v[60:63], v5 offset:16128
	ds_read_b32 v76, v14 offset:1984
	ds_read_b128 v[64:67], v5 offset:24320
	ds_read_b128 v[72:75], v5 offset:40704
	ds_read_b128 v[124:127], v5 offset:7936
	s_nop 0
	s_nop 0
	v_add_f32_e32 v15, v20, v21
	v_pk_fma_f32 v[16:17], v[8:9], v[96:97], v[36:37]
	v_pk_fma_f32 v[18:19], v[6:7], v[98:99], v[38:39]
	v_add_f32_dpp v15, v15, v15 quad_perm:[1,0,3,2] row_mask:0xf bank_mask:0xf bound_ctrl:1
	v_pk_mul_f32 v[24:25], v[112:113], v[8:9]
	v_pk_fma_f32 v[24:25], v[6:7], v[114:115], v[24:25]
	v_add_f32_dpp v15, v15, v15 quad_perm:[2,3,0,1] row_mask:0xf bank_mask:0xf bound_ctrl:1
	v_add_f32_e32 v26, v24, v25
	ds_write_b32 v0, v26 offset:7168
	v_add_f32_dpp v15, v15, v15 row_ror:4 row_mask:0xf bank_mask:0xf bound_ctrl:1
	s_waitcnt lgkmcnt(8)
	v_pk_mul_f32 v[32:33], v[40:41], v[56:57] op_sel_hi:[1,0]
	v_pk_mul_f32 v[34:35], v[42:43], v[56:57] op_sel_hi:[1,0]
	v_add_f32_dpp v22, v15, v15 row_ror:8 row_mask:0xf bank_mask:0xf bound_ctrl:1
	v_pk_fma_f32 v[8:9], v[104:105], v[22:23], v[16:17] op_sel_hi:[1,0,1]
	v_pk_fma_f32 v[6:7], v[106:107], v[22:23], v[18:19] op_sel_hi:[1,0,1]
	v_pk_mul_f32 v[20:21], v[48:49], v[8:9]
	v_pk_fma_f32 v[20:21], v[6:7], v[50:51], v[20:21]
	s_nop 0
	s_nop 0
	v_add_f32_e32 v15, v20, v21
	v_pk_fma_f32 v[16:17], v[8:9], v[44:45], v[32:33]
	v_pk_fma_f32 v[18:19], v[6:7], v[46:47], v[34:35]
	v_add_f32_dpp v15, v15, v15 quad_perm:[1,0,3,2] row_mask:0xf bank_mask:0xf bound_ctrl:1
	v_pk_mul_f32 v[24:25], v[116:117], v[8:9]
	v_pk_fma_f32 v[24:25], v[6:7], v[118:119], v[24:25]
	v_add_f32_dpp v15, v15, v15 quad_perm:[2,3,0,1] row_mask:0xf bank_mask:0xf bound_ctrl:1
	v_add_f32_e32 v26, v24, v25
	ds_write_b32 v0, v26 offset:7424
	v_add_f32_dpp v15, v15, v15 row_ror:4 row_mask:0xf bank_mask:0xf bound_ctrl:1
	s_waitcnt lgkmcnt(2)
	v_pk_mul_f32 v[36:37], v[60:61], v[76:77] op_sel_hi:[1,0]
	v_pk_mul_f32 v[38:39], v[62:63], v[76:77] op_sel_hi:[1,0]
	v_add_f32_dpp v22, v15, v15 row_ror:8 row_mask:0xf bank_mask:0xf bound_ctrl:1
	v_pk_fma_f32 v[8:9], v[52:53], v[22:23], v[16:17] op_sel_hi:[1,0,1]
	v_pk_fma_f32 v[6:7], v[54:55], v[22:23], v[18:19] op_sel_hi:[1,0,1]
	v_pk_mul_f32 v[20:21], v[68:69], v[8:9]
	v_pk_fma_f32 v[20:21], v[6:7], v[70:71], v[20:21]
	s_nop 0
	s_nop 0
	v_add_f32_e32 v15, v20, v21
	v_pk_fma_f32 v[16:17], v[8:9], v[64:65], v[36:37]
	v_pk_fma_f32 v[18:19], v[6:7], v[66:67], v[38:39]
	v_add_f32_dpp v15, v15, v15 quad_perm:[1,0,3,2] row_mask:0xf bank_mask:0xf bound_ctrl:1
	v_pk_mul_f32 v[24:25], v[120:121], v[8:9]
	v_pk_fma_f32 v[24:25], v[6:7], v[122:123], v[24:25]
	v_add_f32_dpp v15, v15, v15 quad_perm:[2,3,0,1] row_mask:0xf bank_mask:0xf bound_ctrl:1
	v_add_f32_e32 v26, v24, v25
	ds_write_b32 v0, v26 offset:7680
	v_add_f32_dpp v15, v15, v15 row_ror:4 row_mask:0xf bank_mask:0xf bound_ctrl:1
	s_nop 1
	v_add_f32_dpp v22, v15, v15 row_ror:8 row_mask:0xf bank_mask:0xf bound_ctrl:1
	v_pk_fma_f32 v[8:9], v[72:73], v[22:23], v[16:17] op_sel_hi:[1,0,1]
	v_pk_fma_f32 v[6:7], v[74:75], v[22:23], v[18:19] op_sel_hi:[1,0,1]
	s_nop 0
	s_nop 0
	v_pk_mul_f32 v[24:25], v[124:125], v[8:9]
	v_pk_fma_f32 v[24:25], v[6:7], v[126:127], v[24:25]
	v_add_u32_e32 v30, -16, v4
	v_ashrrev_i32_e32 v31, 31, v30
	v_add_f32_e32 v26, v24, v25
	ds_write_b32 v0, v26 offset:7936
	v_lshlrev_b64 v[30:31], 11, v[30:31]
	s_nop 0
	v_lshl_add_u64 v[30:31], v[2:3], 0, v[30:31]
	v_mov_b32_e32 v0, v12
	s_waitcnt lgkmcnt(0)
	s_nop 0
	v_add_u32_e32 v0, 0, v0
	ds_read_b128 v[14:17], v0
	ds_read_b128 v[18:21], v0 offset:16
	ds_read_b128 v[22:25], v0 offset:32
	ds_read_b128 v[26:29], v0 offset:48
	s_waitcnt lgkmcnt(2)
	v_pk_add_f32 v[16:17], v[16:17], v[20:21]
	v_pk_add_f32 v[14:15], v[14:15], v[18:19]
	s_waitcnt lgkmcnt(0)
	v_pk_add_f32 v[18:19], v[24:25], v[28:29]
	v_pk_add_f32 v[20:21], v[22:23], v[26:27]
	v_pk_add_f32 v[16:17], v[16:17], v[18:19]
	v_pk_add_f32 v[14:15], v[14:15], v[20:21]
	s_nop 0
	v_add_f32_e32 v5, v14, v15
	v_add_f32_e32 v14, v16, v17
	v_add_f32_e32 v5, v5, v14
	ds_read_b128 v[14:17], v0 offset:4096
	ds_read_b128 v[18:21], v0 offset:4112
	ds_read_b128 v[22:25], v0 offset:4128
	ds_read_b128 v[26:29], v0 offset:4144
	v_cvt_pk_bf16_f32 v5, v5, s0
	global_store_short v[30:31], v5, off
	s_waitcnt lgkmcnt(2)
	v_pk_add_f32 v[16:17], v[16:17], v[20:21]
	v_pk_add_f32 v[14:15], v[14:15], v[18:19]
	s_waitcnt lgkmcnt(0)
	v_pk_add_f32 v[18:19], v[24:25], v[28:29]
	v_pk_add_f32 v[20:21], v[22:23], v[26:27]
	v_pk_add_f32 v[16:17], v[16:17], v[18:19]
	v_pk_add_f32 v[14:15], v[14:15], v[20:21]
	v_add_f32_e32 v5, v16, v17
	v_add_f32_e32 v0, v14, v15
	v_add_f32_e32 v0, v0, v5
	v_ashrrev_i32_e32 v5, 31, v4
	v_lshlrev_b64 v[14:15], 11, v[4:5]
	v_cvt_pk_bf16_f32 v0, v0, s0
	v_lshl_add_u64 v[14:15], v[2:3], 0, v[14:15]
	global_store_short v[14:15], v0, off
	s_waitcnt lgkmcnt(0)
	s_branch .LBB0_905
